# ss row-norm loads preloaded at the tile top also in the two SwiGLU phases (P1, P7); their epilogues no longer wait vmcnt(0)
# speedup vs baseline: 1.0093x; 1.0071x over previous
; #define PG8_WAIT_V(n) asm volatile("s_waitcnt vmcnt(" #n ")" ::: "memory")
; #define PG8_WAIT_L(n) asm volatile("s_waitcnt lgkmcnt(" #n ")" ::: "memory")
; template <class Epi>
; __device__ __forceinline__ void gemm_phase(LAS unsigned char* lds, const Gemm g, const StaticOrder& S, const Epi& E) {
;     ...
;         const bool has_next = S.next(ui + 1, nxt);
;         const char* nA = has_next ? (const char*)g.A + (size_t)nxt.pm * tstepA : cA; const char* nB = has_next ? (const char*)g.Bt + (size_t)nxt.pn * tstepB : cB;
;         for (int t = 0; t < nt; t += 2) {
;             const bool last = (t == nt - 2);
;             const char* a1 = cA + (size_t)(t + 1) * kstepA;
;             const char* a2 = last ? nA : cA + (size_t)(t + 2) * kstepA; const char* b2 = last ? nB : cB + (size_t)(t + 2) * kstep;
;             const char* a3 = a2 + kstepA; const char* b3 = b2 + kstep;
;             PG8_LDB(B0, 0, 0); PG8_LDB(B1, 0, 1); PG8_SCHED; PG8_LDA(At, 0, 0); PG8_STAGE(PG8_SA(1, 1), a1 + hstepA, voffA);
;             PG8_WAIT_V(8); PG8_WAIT_L(0); PG8_BAR; PG8_MMA(0, 0, At, B0); PG8_MMA(0, 1, At, B1); PG8_BAR; PG8_SCHED;
;             PG8_LDA(At, 0, 1); PG8_STAGE(PG8_SB(0, 0), b2, voffB); PG8_STAGE(PG8_SB(0, 1), b2 + hstepB, voffB); PG8_STAGE(PG8_SA(0, 0), a2, voffA);
;             PG8_WAIT_V(8); PG8_WAIT_L(0); PG8_BAR; PG8_MMA(1, 0, At, B0); PG8_MMA(1, 1, At, B1); PG8_BAR; PG8_SCHED;
;             PG8_LDB(B0, 1, 0); PG8_LDB(B1, 1, 1); PG8_SCHED; PG8_LDA(At, 1, 0); PG8_STAGE(PG8_SA(0, 1), a2 + hstepA, voffA);
;             PG8_WAIT_V(8); PG8_WAIT_L(0); PG8_BAR; PG8_MMA(0, 0, At, B0); PG8_MMA(0, 1, At, B1); PG8_BAR; PG8_SCHED;
;             PG8_LDA(At, 1, 1); PG8_STAGE(PG8_SB(1, 0), b3, voffB); PG8_STAGE(PG8_SB(1, 1), b3 + hstepB, voffB); PG8_STAGE(PG8_SA(1, 0), a3, voffA);
;             PG8_WAIT_V(8); PG8_WAIT_L(0); PG8_BAR; PG8_MMA(1, 0, At, B0); PG8_MMA(1, 1, At, B1); PG8_BAR; PG8_SCHED;
;         }
;         if (wr == 0) PG8_BAR;
;         E(acc, cur, wr, wc, fr, fq);
;         if (!has_next) break;
; #pragma unroll
;         for (int a = 0; a < 2; ++a)
; #pragma unroll
;             for (int b = 0; b < 2; ++b)
; #pragma unroll
;                 for (int m = 0; m < 4; ++m)
; #pragma unroll
;                     for (int n = 0; n < 2; ++n) acc[a][b][m][n] = (f32x4){0.f, 0.f, 0.f, 0.f};
;         cur = nxt; cA = nA; cB = nB; ++ui;
.LBB0_451:
	s_ashr_i32 s15, s14, 31
	s_lshl_b64 s[16:17], s[14:15], 19
	v_readlane_b32 s18, v254, 49
	v_readlane_b32 s19, v254, 50
	s_add_u32 s16, s18, s16
	s_addc_u32 s17, s19, s17
	s_and_b64 s[18:19], s[2:3], exec
	s_cselect_b32 s15, s17, s29
	s_cselect_b32 s57, s16, s28
	s_ashr_i32 s13, s12, 31
	s_lshl_b64 s[18:19], s[12:13], 19
	v_readlane_b32 s38, v254, 35
	v_readlane_b32 s39, v254, 36
	s_add_u32 s18, s38, s18
	s_addc_u32 s19, s39, s19
	s_and_b64 s[38:39], s[2:3], exec
	s_cselect_b32 s13, s19, s31
	s_cselect_b32 s58, s18, s30
	s_add_u32 s28, s28, 0x40080
	s_addc_u32 s29, s29, 0
	s_add_u32 s59, s30, 0x100
	v_mov_b32_e32 v0, 0
	s_addc_u32 s60, s31, 0
	s_mov_b32 s61, -2
	v_mov_b32_e32 v1, v0
	v_mov_b32_e32 v2, v0
	v_mov_b32_e32 v3, v0
	v_mov_b32_e32 v8, v0
	v_mov_b32_e32 v9, v0
	v_mov_b32_e32 v10, v0
	v_mov_b32_e32 v11, v0
	v_mov_b32_e32 v16, v0
	v_mov_b32_e32 v17, v0
	v_mov_b32_e32 v18, v0
	v_mov_b32_e32 v19, v0
	v_mov_b32_e32 v24, v0
	v_mov_b32_e32 v25, v0
	v_mov_b32_e32 v26, v0
	v_mov_b32_e32 v27, v0
	v_mov_b32_e32 v32, v0
	v_mov_b32_e32 v33, v0
	v_mov_b32_e32 v34, v0
	v_mov_b32_e32 v35, v0
	v_mov_b32_e32 v40, v0
	v_mov_b32_e32 v41, v0
	v_mov_b32_e32 v42, v0
	v_mov_b32_e32 v43, v0
	v_mov_b32_e32 v48, v0
	v_mov_b32_e32 v49, v0
	v_mov_b32_e32 v50, v0
	v_mov_b32_e32 v51, v0
	v_mov_b32_e32 v56, v0
	v_mov_b32_e32 v57, v0
	v_mov_b32_e32 v58, v0
	v_mov_b32_e32 v59, v0
	v_mov_b32_e32 v4, v0
	v_mov_b32_e32 v5, v0
	v_mov_b32_e32 v6, v0
	v_mov_b32_e32 v7, v0
	v_mov_b32_e32 v12, v0
	v_mov_b32_e32 v13, v0
	v_mov_b32_e32 v14, v0
	v_mov_b32_e32 v15, v0
	v_mov_b32_e32 v20, v0
	v_mov_b32_e32 v21, v0
	v_mov_b32_e32 v22, v0
	v_mov_b32_e32 v23, v0
	v_mov_b32_e32 v28, v0
	v_mov_b32_e32 v29, v0
	v_mov_b32_e32 v30, v0
	v_mov_b32_e32 v31, v0
	v_mov_b32_e32 v36, v0
	v_mov_b32_e32 v37, v0
	v_mov_b32_e32 v38, v0
	v_mov_b32_e32 v39, v0
	v_mov_b32_e32 v44, v0
	v_mov_b32_e32 v45, v0
	v_mov_b32_e32 v46, v0
	v_mov_b32_e32 v47, v0
	v_mov_b32_e32 v52, v0
	v_mov_b32_e32 v53, v0
	v_mov_b32_e32 v54, v0
	v_mov_b32_e32 v55, v0
	v_mov_b32_e32 v60, v0
	v_mov_b32_e32 v61, v0
	v_mov_b32_e32 v62, v0
	v_mov_b32_e32 v63, v0
	v_mov_b32_e32 v64, v0
	v_mov_b32_e32 v65, v0
	v_mov_b32_e32 v66, v0
	v_mov_b32_e32 v67, v0
	v_mov_b32_e32 v72, v0
	v_mov_b32_e32 v73, v0
	v_mov_b32_e32 v74, v0
	v_mov_b32_e32 v75, v0
	v_mov_b32_e32 v80, v0
	v_mov_b32_e32 v81, v0
	v_mov_b32_e32 v82, v0
	v_mov_b32_e32 v83, v0
	v_mov_b32_e32 v88, v0
	v_mov_b32_e32 v89, v0
	v_mov_b32_e32 v90, v0
	v_mov_b32_e32 v91, v0
	v_mov_b32_e32 v96, v0
	v_mov_b32_e32 v97, v0
	v_mov_b32_e32 v98, v0
	v_mov_b32_e32 v99, v0
	v_mov_b32_e32 v104, v0
	v_mov_b32_e32 v105, v0
	v_mov_b32_e32 v106, v0
	v_mov_b32_e32 v107, v0
	v_mov_b32_e32 v112, v0
	v_mov_b32_e32 v113, v0
	v_mov_b32_e32 v114, v0
	v_mov_b32_e32 v115, v0
	v_mov_b32_e32 v120, v0
	v_mov_b32_e32 v121, v0
	v_mov_b32_e32 v122, v0
	v_mov_b32_e32 v123, v0
	v_mov_b32_e32 v68, v0
	v_mov_b32_e32 v69, v0
	v_mov_b32_e32 v70, v0
	v_mov_b32_e32 v71, v0
	v_mov_b32_e32 v76, v0
	v_mov_b32_e32 v77, v0
	v_mov_b32_e32 v78, v0
	v_mov_b32_e32 v79, v0
	v_mov_b32_e32 v84, v0
	v_mov_b32_e32 v85, v0
	v_mov_b32_e32 v86, v0
	v_mov_b32_e32 v87, v0
	v_mov_b32_e32 v92, v0
	v_mov_b32_e32 v93, v0
	v_mov_b32_e32 v94, v0
	v_mov_b32_e32 v95, v0
	v_mov_b32_e32 v100, v0
	v_mov_b32_e32 v101, v0
	v_mov_b32_e32 v102, v0
	v_mov_b32_e32 v103, v0
	v_mov_b32_e32 v108, v0
	v_mov_b32_e32 v109, v0
	v_mov_b32_e32 v110, v0
	v_mov_b32_e32 v111, v0
	v_mov_b32_e32 v116, v0
	v_mov_b32_e32 v117, v0
	v_mov_b32_e32 v118, v0
	v_mov_b32_e32 v119, v0
	v_mov_b32_e32 v124, v0
	v_mov_b32_e32 v125, v0
	v_mov_b32_e32 v126, v0
	v_mov_b32_e32 v127, v0
	v_readlane_b32 s86, v254, 9
	v_readlane_b32 s87, v254, 10
	s_lshl_b32 s85, s0, 8
	s_add_i32 s85, s85, s46
	v_or_b32_e32 v250, s85, v144
	v_ashrrev_i32_e32 v251, 31, v250
	v_lshl_add_u64 v[252:253], v[250:251], 2, s[86:87]
	global_load_dword v235, v[252:253], off
	global_load_dword v236, v[252:253], off offset:64
	global_load_dword v237, v[252:253], off offset:128
	global_load_dword v238, v[252:253], off offset:192
	global_load_dword v239, v[252:253], off offset:512
	global_load_dword v240, v[252:253], off offset:576
	global_load_dword v241, v[252:253], off offset:640
	global_load_dword v242, v[252:253], off offset:704

; __device__ __forceinline__ unsigned cvt_pk_bf16(float lo, float hi) { unsigned r; asm volatile("v_cvt_pk_bf16_f32 %0, %1, %2" : "=v"(r) : "v"(lo), "v"(hi)); return r; }
; __device__ __forceinline__ float fast_sigmoid(float a) { return __builtin_amdgcn_rcpf(1.0f + __expf(-a)); }
;     __device__ __forceinline__ void operator()(const Acc& acc, const Unit& u, int wr, int wc, int fr, int fq) const {
;     ...
; #pragma unroll
;         for (int ai = 0; ai < 2; ++ai)
; #pragma unroll
;             for (int m = 0; m < 4; ++m) {
;                 const int row = u.pm * 256 + ai * 128 + wr * 64 + m * 16 + fr;
;                 const float rs = rsqrtf(ssv[ai][m] * (1.0f / DM) + EPS);
;                 bf16_t* dst = act + ((size_t)((row >> 8) * (DFF / 64) + u.pn * 2 + (wc >> 1)) * 256 + (row & 255)) * 64 + (wc & 1) * 32 + fq * 8;
;                 u32x4 w;
; #pragma unroll
;                 for (int n = 0; n < 2; ++n) {
;                     const f32x4 a = acc[ai][0][m][n] * rs, b = acc[ai][1][m][n] * rs; f32x4 v;
; #pragma unroll
;                     for (int j = 0; j < 4; ++j) v[j] = a[j] * fast_sigmoid(a[j]) * b[j];
;                     if (n == 0) { w.x = cvt_pk_bf16(v[0], v[1]); w.y = cvt_pk_bf16(v[2], v[3]); } else { w.z = cvt_pk_bf16(v[0], v[1]); w.w = cvt_pk_bf16(v[2], v[3]); }
;                 }
;                 *(u32x4*)dst = w;
;             }
.LBB0_455:
	s_lshl_b32 s13, s0, 8
	s_add_i32 s13, s13, s46
	v_or_b32_e32 v150, s13, v144
	v_readlane_b32 s28, v254, 9
	v_ashrrev_i32_e32 v151, 31, v150
	v_readlane_b32 s29, v254, 10
	v_readlane_b32 s30, v254, 11
	v_readlane_b32 s31, v254, 12
	v_lshl_add_u64 v[154:155], v[150:151], 2, s[28:29]
	v_mov_b32_e32 v156, v235
	v_mov_b32_e32 v160, v236
	v_mov_b32_e32 v161, v237
	v_mov_b32_e32 v162, v238
	v_mov_b32_e32 v153, v239
	v_mov_b32_e32 v152, v240
	v_mov_b32_e32 v151, v241
	v_mov_b32_e32 v150, v242
	s_nop 0
	v_fmamk_f32 v154, v156, 0x3a800000, v149
	v_mul_f32_e32 v155, 0x4b800000, v154
	v_cmp_gt_f32_e32 vcc, s54, v154
	v_mov_b32_e32 v158, v123
	v_mov_b32_e32 v159, v127
	v_cndmask_b32_e32 v154, v154, v155, vcc
	v_rsq_f32_e32 v154, v154
	s_lshl_b32 s0, s1, 1
	s_or_b32 s15, s0, s49
	s_ashr_i32 s0, s13, 8
	v_mul_f32_e32 v155, 0x45800000, v154
	v_cndmask_b32_e32 v154, v154, v155, vcc
	v_pk_mul_f32 v[158:159], v[158:159], v[154:155] op_sel_hi:[1,0]
	s_mul_i32 s0, s0, 44
	v_mul_f32_e32 v123, 0xbfb8aa3b, v159
	v_exp_f32_e32 v155, v123
	v_mov_b32_e32 v123, v126
	s_add_i32 s0, s0, s15
	s_ashr_i32 s1, s0, 31
	v_pk_mul_f32 v[122:123], v[122:123], v[154:155] op_sel_hi:[1,0]
	v_add_f32_e32 v155, 1.0, v155
	v_mul_f32_e32 v126, 0xbfb8aa3b, v123
	v_exp_f32_e32 v163, v126
	s_lshl_b64 s[0:1], s[0:1], 15
	v_rcp_f32_e32 v155, v155
	v_lshl_add_u64 v[156:157], v[134:135], 0, s[0:1]
	v_lshl_add_u64 v[126:127], v[156:157], 0, s[4:5]
	v_add_f32_e32 v156, 1.0, v163
	v_rcp_f32_e32 v163, v156
	v_mov_b32_e32 v156, v121
	v_mov_b32_e32 v157, v125
	v_pk_mul_f32 v[156:157], v[156:157], v[154:155] op_sel_hi:[1,0]
	v_mul_f32_e32 v125, v159, v155
	v_mul_f32_e32 v121, 0xbfb8aa3b, v157
	v_exp_f32_e32 v121, v121
	v_mul_f32_e32 v123, v123, v163
	v_mul_f32_e32 v125, v158, v125
	v_mul_f32_e32 v158, v122, v123
	v_add_f32_e32 v121, 1.0, v121
	v_rcp_f32_e32 v155, v121
	v_mov_b32_e32 v121, v124
	v_mov_b32_e32 v123, v119
	s_addk_i32 s13, 0x80
	v_pk_mul_f32 v[120:121], v[120:121], v[154:155] op_sel_hi:[1,0]
	v_mul_f32_e32 v122, v157, v155
	v_mul_f32_e32 v124, 0xbfb8aa3b, v121
	v_exp_f32_e32 v124, v124
	v_mul_f32_e32 v155, v156, v122
	v_readlane_b32 s28, v254, 51
	v_readlane_b32 s29, v254, 52
	v_add_f32_e32 v122, 1.0, v124
	v_rcp_f32_e32 v124, v122
	v_mov_b32_e32 v122, v115
	v_pk_mul_f32 v[122:123], v[122:123], v[154:155] op_sel_hi:[1,0]
	v_mul_f32_e32 v119, v121, v124
	v_mul_f32_e32 v115, 0xbfb8aa3b, v123
	v_exp_f32_e32 v115, v115
	v_mul_f32_e32 v119, v120, v119
	v_cvt_pk_bf16_f32 v120, v119, v155
	v_cvt_pk_bf16_f32 v121, v158, v125
	v_add_f32_e32 v115, 1.0, v115
	v_rcp_f32_e32 v119, v115
	v_mov_b32_e32 v115, v118
	v_pk_mul_f32 v[114:115], v[114:115], v[154:155] op_sel_hi:[1,0]
	v_mul_f32_e32 v119, v123, v119
	v_mul_f32_e32 v118, 0xbfb8aa3b, v115
	v_exp_f32_e32 v118, v118
	v_mul_f32_e32 v123, v122, v119
	v_mov_b32_e32 v119, v117
	v_add_f32_e32 v118, 1.0, v118
	v_rcp_f32_e32 v122, v118
	v_mov_b32_e32 v118, v113
	v_pk_mul_f32 v[118:119], v[118:119], v[154:155] op_sel_hi:[1,0]
	v_mul_f32_e32 v115, v115, v122
	v_mul_f32_e32 v113, 0xbfb8aa3b, v119
	v_exp_f32_e32 v117, v113
	v_mov_b32_e32 v113, v116
	v_pk_mul_f32 v[112:113], v[112:113], v[154:155] op_sel_hi:[1,0]
	v_mul_f32_e32 v114, v114, v115
	v_mul_f32_e32 v116, 0xbfb8aa3b, v113
	v_exp_f32_e32 v116, v116
	v_add_f32_e32 v117, 1.0, v117
	v_rcp_f32_e32 v117, v117
	v_add_f32_e32 v116, 1.0, v116
	v_rcp_f32_e32 v116, v116
	v_mul_f32_e32 v115, v119, v117
	v_mul_f32_e32 v115, v118, v115
	v_mov_b32_e32 v117, v111
	v_mul_f32_e32 v113, v113, v116
	v_mul_f32_e32 v112, v112, v113
	v_fmamk_f32 v113, v160, 0x3a800000, v149
	v_mul_f32_e32 v116, 0x4b800000, v113
	v_cmp_gt_f32_e32 vcc, s54, v113
	v_cvt_pk_bf16_f32 v122, v112, v115
	v_cvt_pk_bf16_f32 v123, v114, v123
	s_nop 1
	v_cndmask_b32_e32 v113, v113, v116, vcc
	v_rsq_f32_e32 v116, v113
	v_lshl_add_u64 v[112:113], v[126:127], 0, v[132:133]
	global_store_dwordx4 v[112:113], v[120:123], off
	v_mul_f32_e32 v114, 0x45800000, v116
	v_cndmask_b32_e32 v114, v116, v114, vcc
	v_mov_b32_e32 v116, v107
	v_pk_mul_f32 v[116:117], v[116:117], v[114:115] op_sel_hi:[1,0]
	s_nop 0
	v_mul_f32_e32 v107, 0xbfb8aa3b, v117
	v_exp_f32_e32 v111, v107
	v_mov_b32_e32 v107, v110
	v_pk_mul_f32 v[106:107], v[106:107], v[114:115] op_sel_hi:[1,0]
	v_add_f32_e32 v111, 1.0, v111
	v_mul_f32_e32 v110, 0xbfb8aa3b, v107
	v_exp_f32_e32 v110, v110
	v_rcp_f32_e32 v115, v111
	v_mov_b32_e32 v111, v109
	v_add_f32_e32 v110, 1.0, v110
	v_rcp_f32_e32 v118, v110
	v_mov_b32_e32 v110, v105
	v_pk_mul_f32 v[110:111], v[110:111], v[114:115] op_sel_hi:[1,0]
	v_mul_f32_e32 v109, v117, v115
	v_mul_f32_e32 v105, 0xbfb8aa3b, v111
	v_exp_f32_e32 v105, v105
	v_mul_f32_e32 v107, v107, v118
	v_mul_f32_e32 v109, v116, v109
	v_mul_f32_e32 v116, v106, v107
	v_add_f32_e32 v105, 1.0, v105
	v_rcp_f32_e32 v115, v105
	v_mov_b32_e32 v105, v108
	v_mov_b32_e32 v107, v103
	v_pk_mul_f32 v[104:105], v[104:105], v[114:115] op_sel_hi:[1,0]
	s_nop 0
	v_mul_f32_e32 v108, 0xbfb8aa3b, v105
	v_exp_f32_e32 v108, v108
	v_mul_f32_e32 v106, v111, v115
	v_mul_f32_e32 v110, v110, v106
	v_add_f32_e32 v106, 1.0, v108
	v_rcp_f32_e32 v108, v106
	v_mov_b32_e32 v106, v99
	v_pk_mul_f32 v[106:107], v[106:107], v[114:115] op_sel_hi:[1,0]
	v_mul_f32_e32 v103, v105, v108
	v_mul_f32_e32 v99, 0xbfb8aa3b, v107
	v_exp_f32_e32 v99, v99
	v_mul_f32_e32 v103, v104, v103
	v_cvt_pk_bf16_f32 v104, v103, v110
	v_cvt_pk_bf16_f32 v105, v116, v109
	v_add_f32_e32 v99, 1.0, v99
	v_rcp_f32_e32 v103, v99
	v_mov_b32_e32 v99, v102
	v_pk_mul_f32 v[98:99], v[98:99], v[114:115] op_sel_hi:[1,0]
	v_mul_f32_e32 v103, v107, v103
	v_mul_f32_e32 v102, 0xbfb8aa3b, v99
	v_exp_f32_e32 v102, v102
	v_mul_f32_e32 v107, v106, v103
; __device__ __forceinline__ unsigned cvt_pk_bf16(float lo, float hi) { unsigned r; asm volatile("v_cvt_pk_bf16_f32 %0, %1, %2" : "=v"(r) : "v"(lo), "v"(hi)); return r; }
; __device__ __forceinline__ float fast_sigmoid(float a) { return __builtin_amdgcn_rcpf(1.0f + __expf(-a)); }
;     __device__ __forceinline__ void operator()(const Acc& acc, const Unit& u, int wr, int wc, int fr, int fq) const {
;     ...
; #pragma unroll
;         for (int ai = 0; ai < 2; ++ai)
; #pragma unroll
;             for (int m = 0; m < 4; ++m) {
;                 const int row = u.pm * 256 + ai * 128 + wr * 64 + m * 16 + fr;
;                 const float rs = rsqrtf(ssv[ai][m] * (1.0f / DM) + EPS);
;                 bf16_t* dst = act + ((size_t)((row >> 8) * (DFF / 64) + u.pn * 2 + (wc >> 1)) * 256 + (row & 255)) * 64 + (wc & 1) * 32 + fq * 8;
;                 u32x4 w;
; #pragma unroll
;                 for (int n = 0; n < 2; ++n) {
;                     const f32x4 a = acc[ai][0][m][n] * rs, b = acc[ai][1][m][n] * rs; f32x4 v;
; #pragma unroll
;                     for (int j = 0; j < 4; ++j) v[j] = a[j] * fast_sigmoid(a[j]) * b[j];
;                     if (n == 0) { w.x = cvt_pk_bf16(v[0], v[1]); w.y = cvt_pk_bf16(v[2], v[3]); } else { w.z = cvt_pk_bf16(v[0], v[1]); w.w = cvt_pk_bf16(v[2], v[3]); }
;                 }
;                 *(u32x4*)dst = w;
;             }
	v_mov_b32_e32 v103, v101
	v_add_f32_e32 v102, 1.0, v102
	v_rcp_f32_e32 v106, v102
	v_mov_b32_e32 v102, v97
	v_pk_mul_f32 v[102:103], v[102:103], v[114:115] op_sel_hi:[1,0]
	v_mul_f32_e32 v99, v99, v106
	v_mul_f32_e32 v97, 0xbfb8aa3b, v103
	v_exp_f32_e32 v101, v97
	v_mov_b32_e32 v97, v100
	v_pk_mul_f32 v[96:97], v[96:97], v[114:115] op_sel_hi:[1,0]
	v_mul_f32_e32 v98, v98, v99
	v_mul_f32_e32 v100, 0xbfb8aa3b, v97
	v_exp_f32_e32 v100, v100
	v_add_f32_e32 v101, 1.0, v101
	v_rcp_f32_e32 v101, v101
	v_add_f32_e32 v100, 1.0, v100
	v_rcp_f32_e32 v100, v100
	v_mul_f32_e32 v99, v103, v101
	v_mul_f32_e32 v99, v102, v99
	v_mul_f32_e32 v97, v97, v100
	v_fmamk_f32 v100, v161, 0x3a800000, v149
	v_mul_f32_e32 v101, 0x4b800000, v100
	v_cmp_gt_f32_e32 vcc, s54, v100
	v_mul_f32_e32 v96, v96, v97
	v_cvt_pk_bf16_f32 v106, v96, v99
	v_cvt_pk_bf16_f32 v107, v98, v107
	v_mov_b32_e32 v98, v91
	v_cndmask_b32_e32 v100, v100, v101, vcc
	v_rsq_f32_e32 v100, v100
	v_mov_b32_e32 v99, v95
	global_store_dwordx4 v[112:113], v[104:107], off offset:2048
	v_mul_f32_e32 v96, 0x45800000, v100
	v_cndmask_b32_e32 v96, v100, v96, vcc
	v_pk_mul_f32 v[98:99], v[98:99], v[96:97] op_sel_hi:[1,0]
	s_nop 0
	v_mul_f32_e32 v91, 0xbfb8aa3b, v99
	v_exp_f32_e32 v95, v91
	v_mov_b32_e32 v91, v94
	v_pk_mul_f32 v[90:91], v[90:91], v[96:97] op_sel_hi:[1,0]
	v_add_f32_e32 v95, 1.0, v95
	v_mul_f32_e32 v94, 0xbfb8aa3b, v91
	v_exp_f32_e32 v94, v94
	v_rcp_f32_e32 v97, v95
	v_mov_b32_e32 v95, v93
	v_add_f32_e32 v94, 1.0, v94
	v_rcp_f32_e32 v100, v94
	v_mov_b32_e32 v94, v89
	v_pk_mul_f32 v[94:95], v[94:95], v[96:97] op_sel_hi:[1,0]
	v_mul_f32_e32 v93, v99, v97
	v_mul_f32_e32 v89, 0xbfb8aa3b, v95
	v_exp_f32_e32 v89, v89
	v_mul_f32_e32 v91, v91, v100
	v_mul_f32_e32 v93, v98, v93
	v_mul_f32_e32 v98, v90, v91
	v_add_f32_e32 v89, 1.0, v89
	v_rcp_f32_e32 v97, v89
	v_mov_b32_e32 v89, v92
	v_mov_b32_e32 v91, v87
	v_pk_mul_f32 v[88:89], v[88:89], v[96:97] op_sel_hi:[1,0]
	s_nop 0
	v_mul_f32_e32 v92, 0xbfb8aa3b, v89
	v_exp_f32_e32 v92, v92
	v_mul_f32_e32 v90, v95, v97
	v_mul_f32_e32 v94, v94, v90
	v_add_f32_e32 v90, 1.0, v92
	v_rcp_f32_e32 v92, v90
	v_mov_b32_e32 v90, v83
	v_pk_mul_f32 v[90:91], v[90:91], v[96:97] op_sel_hi:[1,0]
	v_mul_f32_e32 v87, v89, v92
	v_mul_f32_e32 v83, 0xbfb8aa3b, v91
	v_exp_f32_e32 v83, v83
	v_mul_f32_e32 v87, v88, v87
	v_cvt_pk_bf16_f32 v88, v87, v94
	v_cvt_pk_bf16_f32 v89, v98, v93
	v_add_f32_e32 v83, 1.0, v83
	v_rcp_f32_e32 v87, v83
	v_mov_b32_e32 v83, v86
	v_pk_mul_f32 v[82:83], v[82:83], v[96:97] op_sel_hi:[1,0]
	v_mul_f32_e32 v87, v91, v87
	v_mul_f32_e32 v86, 0xbfb8aa3b, v83
	v_exp_f32_e32 v86, v86
	v_mul_f32_e32 v91, v90, v87
	v_mov_b32_e32 v87, v85
	v_add_f32_e32 v86, 1.0, v86
	v_rcp_f32_e32 v90, v86
	v_mov_b32_e32 v86, v81
	v_pk_mul_f32 v[86:87], v[86:87], v[96:97] op_sel_hi:[1,0]
	v_mul_f32_e32 v83, v83, v90
	v_mul_f32_e32 v81, 0xbfb8aa3b, v87
	v_exp_f32_e32 v85, v81
	v_mov_b32_e32 v81, v84
	v_pk_mul_f32 v[80:81], v[80:81], v[96:97] op_sel_hi:[1,0]
	v_mul_f32_e32 v82, v82, v83
	v_mul_f32_e32 v84, 0xbfb8aa3b, v81
	v_exp_f32_e32 v84, v84
	v_add_f32_e32 v85, 1.0, v85
	v_rcp_f32_e32 v85, v85
	v_add_f32_e32 v84, 1.0, v84
	v_rcp_f32_e32 v84, v84
	v_mul_f32_e32 v83, v87, v85
	v_mul_f32_e32 v83, v86, v83
	v_mov_b32_e32 v85, v79
	v_mul_f32_e32 v81, v81, v84
	v_mul_f32_e32 v80, v80, v81
	v_cvt_pk_bf16_f32 v90, v80, v83
	v_fmamk_f32 v80, v162, 0x3a800000, v149
	v_mul_f32_e32 v81, 0x4b800000, v80
	v_cmp_gt_f32_e32 vcc, s54, v80
	v_cvt_pk_bf16_f32 v91, v82, v91
	v_mov_b32_e32 v84, v75
	s_nop 0
	v_cndmask_b32_e32 v80, v80, v81, vcc
	v_rsq_f32_e32 v82, v80
	v_add_co_u32_e64 v80, s[0:1], s55, v112
	v_mul_f32_e32 v83, 0x45800000, v82
	v_cndmask_b32_e32 v82, v82, v83, vcc
	v_pk_mul_f32 v[84:85], v[84:85], v[82:83] op_sel_hi:[1,0]
	v_addc_co_u32_e64 v81, s[0:1], 0, v113, s[0:1]
	v_mul_f32_e32 v75, 0xbfb8aa3b, v85
	v_exp_f32_e32 v79, v75
	v_mov_b32_e32 v75, v78
	v_pk_mul_f32 v[74:75], v[74:75], v[82:83] op_sel_hi:[1,0]
	global_store_dwordx4 v[80:81], v[88:91], off
	v_mul_f32_e32 v78, 0xbfb8aa3b, v75
	v_exp_f32_e32 v78, v78
	v_add_f32_e32 v79, 1.0, v79
	v_rcp_f32_e32 v83, v79
	v_mov_b32_e32 v79, v77
	v_add_f32_e32 v78, 1.0, v78
	v_rcp_f32_e32 v86, v78
	v_mov_b32_e32 v78, v73
	v_pk_mul_f32 v[78:79], v[78:79], v[82:83] op_sel_hi:[1,0]
	v_mul_f32_e32 v77, v85, v83
	v_mul_f32_e32 v73, 0xbfb8aa3b, v79
	v_exp_f32_e32 v73, v73
	v_mul_f32_e32 v75, v75, v86
	v_mul_f32_e32 v77, v84, v77
	v_mul_f32_e32 v84, v74, v75
	v_add_f32_e32 v73, 1.0, v73
	v_rcp_f32_e32 v83, v73
	v_mov_b32_e32 v73, v76
	v_mov_b32_e32 v75, v71
	s_ashr_i32 s0, s13, 8
	v_pk_mul_f32 v[72:73], v[72:73], v[82:83] op_sel_hi:[1,0]
	v_mul_f32_e32 v74, v79, v83
	v_mul_f32_e32 v76, 0xbfb8aa3b, v73
	v_exp_f32_e32 v76, v76
	v_mul_f32_e32 v78, v78, v74
	s_and_b32 s13, s13, 0xc0
	s_mul_i32 s0, s0, 44
	v_add_f32_e32 v74, 1.0, v76
	v_rcp_f32_e32 v76, v74
	v_mov_b32_e32 v74, v67
	v_pk_mul_f32 v[74:75], v[74:75], v[82:83] op_sel_hi:[1,0]
	s_add_i32 s0, s0, s15
	v_mul_f32_e32 v67, 0xbfb8aa3b, v75
	v_exp_f32_e32 v67, v67
	v_mul_f32_e32 v71, v73, v76
	v_mul_f32_e32 v71, v72, v71
	v_cvt_pk_bf16_f32 v72, v71, v78
	v_add_f32_e32 v67, 1.0, v67
	v_rcp_f32_e32 v71, v67
	v_mov_b32_e32 v67, v70
	v_pk_mul_f32 v[66:67], v[66:67], v[82:83] op_sel_hi:[1,0]
	v_cvt_pk_bf16_f32 v73, v84, v77
	v_mul_f32_e32 v71, v75, v71
	v_mul_f32_e32 v70, 0xbfb8aa3b, v67
	v_exp_f32_e32 v70, v70
	v_mul_f32_e32 v75, v74, v71
	v_mov_b32_e32 v71, v69
	s_ashr_i32 s1, s0, 31
	v_add_f32_e32 v70, 1.0, v70
	v_rcp_f32_e32 v74, v70
	v_mov_b32_e32 v70, v65
	v_pk_mul_f32 v[70:71], v[70:71], v[82:83] op_sel_hi:[1,0]
	s_lshl_b64 s[0:1], s[0:1], 15
	v_mul_f32_e32 v65, 0xbfb8aa3b, v71
; __device__ __forceinline__ unsigned cvt_pk_bf16(float lo, float hi) { unsigned r; asm volatile("v_cvt_pk_bf16_f32 %0, %1, %2" : "=v"(r) : "v"(lo), "v"(hi)); return r; }
; __device__ __forceinline__ float fast_sigmoid(float a) { return __builtin_amdgcn_rcpf(1.0f + __expf(-a)); }
;     __device__ __forceinline__ void operator()(const Acc& acc, const Unit& u, int wr, int wc, int fr, int fq) const {
;     ...
; #pragma unroll
;         for (int ai = 0; ai < 2; ++ai)
; #pragma unroll
;             for (int m = 0; m < 4; ++m) {
;                 const int row = u.pm * 256 + ai * 128 + wr * 64 + m * 16 + fr;
;                 const float rs = rsqrtf(ssv[ai][m] * (1.0f / DM) + EPS);
;                 bf16_t* dst = act + ((size_t)((row >> 8) * (DFF / 64) + u.pn * 2 + (wc >> 1)) * 256 + (row & 255)) * 64 + (wc & 1) * 32 + fq * 8;
;                 u32x4 w;
; #pragma unroll
;                 for (int n = 0; n < 2; ++n) {
;                     const f32x4 a = acc[ai][0][m][n] * rs, b = acc[ai][1][m][n] * rs; f32x4 v;
; #pragma unroll
;                     for (int j = 0; j < 4; ++j) v[j] = a[j] * fast_sigmoid(a[j]) * b[j];
;                     if (n == 0) { w.x = cvt_pk_bf16(v[0], v[1]); w.y = cvt_pk_bf16(v[2], v[3]); } else { w.z = cvt_pk_bf16(v[0], v[1]); w.w = cvt_pk_bf16(v[2], v[3]); }
;                 }
;                 *(u32x4*)dst = w;
;             }
	v_exp_f32_e32 v69, v65
	v_mov_b32_e32 v65, v68
	v_pk_mul_f32 v[64:65], v[64:65], v[82:83] op_sel_hi:[1,0]
	v_mul_f32_e32 v67, v67, v74
	v_mul_f32_e32 v68, 0xbfb8aa3b, v65
	v_exp_f32_e32 v68, v68
	v_add_f32_e32 v69, 1.0, v69
	v_rcp_f32_e32 v69, v69
	v_mul_f32_e32 v66, v66, v67
	v_add_f32_e32 v68, 1.0, v68
	v_rcp_f32_e32 v68, v68
	v_mul_f32_e32 v67, v71, v69
	v_mul_f32_e32 v67, v70, v67
	v_mov_b32_e32 v69, v63
	v_mul_f32_e32 v65, v65, v68
	v_mul_f32_e32 v64, v64, v65
	v_cvt_pk_bf16_f32 v74, v64, v67
	v_fmamk_f32 v64, v153, 0x3a800000, v149
	v_mul_f32_e32 v65, 0x4b800000, v64
	v_cmp_gt_f32_e32 vcc, s54, v64
	v_cvt_pk_bf16_f32 v75, v66, v75
	v_mov_b32_e32 v68, v59
	s_add_u32 s0, s28, s0
	v_cndmask_b32_e32 v64, v64, v65, vcc
	v_rsq_f32_e32 v64, v64
	v_or_b32_e32 v65, s13, v144
	s_addc_u32 s1, s29, s1
	v_mov_b32_e32 v67, v133
	v_mul_f32_e32 v66, 0x45800000, v64
	v_cndmask_b32_e32 v64, v64, v66, vcc
	v_pk_mul_f32 v[68:69], v[68:69], v[64:65] op_sel_hi:[1,0]
	v_lshlrev_b32_e32 v66, 7, v65
	v_mul_f32_e32 v59, 0xbfb8aa3b, v69
	v_exp_f32_e32 v65, v59
	v_mov_b32_e32 v59, v62
	v_lshl_add_u64 v[66:67], s[0:1], 0, v[66:67]
	global_store_dwordx4 v[80:81], v[72:75], off offset:2048
	v_pk_mul_f32 v[58:59], v[58:59], v[64:65] op_sel_hi:[1,0]
	v_add_f32_e32 v65, 1.0, v65
	v_mul_f32_e32 v62, 0xbfb8aa3b, v59
	v_exp_f32_e32 v70, v62
	v_rcp_f32_e32 v65, v65
	v_lshl_add_u64 v[62:63], v[66:67], 0, s[4:5]
	v_mov_b32_e32 v67, v61
	v_add_f32_e32 v66, 1.0, v70
	v_rcp_f32_e32 v70, v66
	v_mov_b32_e32 v66, v57
	v_pk_mul_f32 v[66:67], v[66:67], v[64:65] op_sel_hi:[1,0]
	v_mul_f32_e32 v61, v69, v65
	v_mul_f32_e32 v57, 0xbfb8aa3b, v67
	v_exp_f32_e32 v57, v57
	v_mul_f32_e32 v59, v59, v70
	v_mul_f32_e32 v61, v68, v61
	v_mul_f32_e32 v68, v58, v59
	v_add_f32_e32 v57, 1.0, v57
	v_rcp_f32_e32 v65, v57
	v_mov_b32_e32 v57, v60
	v_mov_b32_e32 v59, v55
	v_pk_mul_f32 v[56:57], v[56:57], v[64:65] op_sel_hi:[1,0]
	s_nop 0
	v_mul_f32_e32 v60, 0xbfb8aa3b, v57
	v_exp_f32_e32 v60, v60
	v_mul_f32_e32 v58, v67, v65
	v_mul_f32_e32 v65, v66, v58
	v_add_f32_e32 v58, 1.0, v60
	v_rcp_f32_e32 v60, v58
	v_mov_b32_e32 v58, v51
	v_pk_mul_f32 v[58:59], v[58:59], v[64:65] op_sel_hi:[1,0]
	v_mul_f32_e32 v55, v57, v60
	v_mul_f32_e32 v51, 0xbfb8aa3b, v59
	v_exp_f32_e32 v51, v51
	v_mul_f32_e32 v55, v56, v55
	v_cvt_pk_bf16_f32 v56, v55, v65
	v_cvt_pk_bf16_f32 v57, v68, v61
	v_add_f32_e32 v51, 1.0, v51
	v_rcp_f32_e32 v55, v51
	v_mov_b32_e32 v51, v54
	v_pk_mul_f32 v[50:51], v[50:51], v[64:65] op_sel_hi:[1,0]
	v_mul_f32_e32 v55, v59, v55
	v_mul_f32_e32 v54, 0xbfb8aa3b, v51
	v_exp_f32_e32 v54, v54
	v_mul_f32_e32 v59, v58, v55
	v_mov_b32_e32 v55, v53
	v_add_f32_e32 v54, 1.0, v54
	v_rcp_f32_e32 v58, v54
	v_mov_b32_e32 v54, v49
	v_pk_mul_f32 v[54:55], v[54:55], v[64:65] op_sel_hi:[1,0]
	v_mul_f32_e32 v51, v51, v58
	v_mul_f32_e32 v49, 0xbfb8aa3b, v55
	v_exp_f32_e32 v53, v49
	v_mov_b32_e32 v49, v52
	v_pk_mul_f32 v[48:49], v[48:49], v[64:65] op_sel_hi:[1,0]
	v_mul_f32_e32 v50, v50, v51
	v_mul_f32_e32 v52, 0xbfb8aa3b, v49
	v_exp_f32_e32 v52, v52
	v_add_f32_e32 v53, 1.0, v53
	v_rcp_f32_e32 v53, v53
	v_add_f32_e32 v52, 1.0, v52
	v_rcp_f32_e32 v52, v52
	v_mul_f32_e32 v51, v55, v53
	v_mul_f32_e32 v51, v54, v51
	v_mov_b32_e32 v53, v47
	v_mul_f32_e32 v49, v49, v52
	v_mul_f32_e32 v48, v48, v49
	v_fmamk_f32 v49, v152, 0x3a800000, v149
	v_mul_f32_e32 v52, 0x4b800000, v49
	v_cmp_gt_f32_e32 vcc, s54, v49
	v_cvt_pk_bf16_f32 v58, v48, v51
	v_cvt_pk_bf16_f32 v59, v50, v59
	s_nop 1
	v_cndmask_b32_e32 v49, v49, v52, vcc
	v_rsq_f32_e32 v52, v49
	v_lshl_add_u64 v[48:49], v[62:63], 0, v[132:133]
	global_store_dwordx4 v[48:49], v[56:59], off
	v_mul_f32_e32 v50, 0x45800000, v52
	v_cndmask_b32_e32 v50, v52, v50, vcc
	v_mov_b32_e32 v52, v43
	v_pk_mul_f32 v[52:53], v[52:53], v[50:51] op_sel_hi:[1,0]
	s_nop 0
	v_mul_f32_e32 v43, 0xbfb8aa3b, v53
	v_exp_f32_e32 v47, v43
	v_mov_b32_e32 v43, v46
	v_pk_mul_f32 v[42:43], v[42:43], v[50:51] op_sel_hi:[1,0]
	v_add_f32_e32 v47, 1.0, v47
	v_mul_f32_e32 v46, 0xbfb8aa3b, v43
	v_exp_f32_e32 v46, v46
	v_rcp_f32_e32 v51, v47
	v_mov_b32_e32 v47, v45
	v_add_f32_e32 v46, 1.0, v46
	v_rcp_f32_e32 v54, v46
	v_mov_b32_e32 v46, v41
	v_pk_mul_f32 v[46:47], v[46:47], v[50:51] op_sel_hi:[1,0]
	v_mul_f32_e32 v45, v53, v51
	v_mul_f32_e32 v41, 0xbfb8aa3b, v47
	v_exp_f32_e32 v41, v41
	v_mul_f32_e32 v43, v43, v54
	v_mul_f32_e32 v45, v52, v45
	v_mul_f32_e32 v52, v42, v43
	v_add_f32_e32 v41, 1.0, v41
	v_rcp_f32_e32 v51, v41
	v_mov_b32_e32 v41, v44
	v_mov_b32_e32 v43, v39
	v_pk_mul_f32 v[40:41], v[40:41], v[50:51] op_sel_hi:[1,0]
	s_nop 0
	v_mul_f32_e32 v44, 0xbfb8aa3b, v41
	v_exp_f32_e32 v44, v44
	v_mul_f32_e32 v42, v47, v51
	v_mul_f32_e32 v46, v46, v42
	v_add_f32_e32 v42, 1.0, v44
	v_rcp_f32_e32 v44, v42
	v_mov_b32_e32 v42, v35
	v_pk_mul_f32 v[42:43], v[42:43], v[50:51] op_sel_hi:[1,0]
	v_mul_f32_e32 v39, v41, v44
	v_mul_f32_e32 v35, 0xbfb8aa3b, v43
	v_exp_f32_e32 v35, v35
	v_mul_f32_e32 v39, v40, v39
	v_cvt_pk_bf16_f32 v40, v39, v46
	v_cvt_pk_bf16_f32 v41, v52, v45
	v_add_f32_e32 v35, 1.0, v35
	v_rcp_f32_e32 v39, v35
	v_mov_b32_e32 v35, v38
	v_pk_mul_f32 v[34:35], v[34:35], v[50:51] op_sel_hi:[1,0]
	v_mul_f32_e32 v39, v43, v39
	v_mul_f32_e32 v38, 0xbfb8aa3b, v35
	v_exp_f32_e32 v38, v38
	v_mul_f32_e32 v43, v42, v39
	v_mov_b32_e32 v39, v37
	v_add_f32_e32 v38, 1.0, v38
	v_rcp_f32_e32 v42, v38
	v_mov_b32_e32 v38, v33
	v_pk_mul_f32 v[38:39], v[38:39], v[50:51] op_sel_hi:[1,0]
	v_mul_f32_e32 v35, v35, v42
	v_mul_f32_e32 v33, 0xbfb8aa3b, v39
	v_exp_f32_e32 v37, v33
	v_mov_b32_e32 v33, v36
	v_pk_mul_f32 v[32:33], v[32:33], v[50:51] op_sel_hi:[1,0]
	v_mul_f32_e32 v34, v34, v35
	v_mul_f32_e32 v36, 0xbfb8aa3b, v33
	v_exp_f32_e32 v36, v36
; __device__ __forceinline__ unsigned cvt_pk_bf16(float lo, float hi) { unsigned r; asm volatile("v_cvt_pk_bf16_f32 %0, %1, %2" : "=v"(r) : "v"(lo), "v"(hi)); return r; }
; __device__ __forceinline__ float fast_sigmoid(float a) { return __builtin_amdgcn_rcpf(1.0f + __expf(-a)); }
;     __device__ __forceinline__ void operator()(const Acc& acc, const Unit& u, int wr, int wc, int fr, int fq) const {
;     ...
; #pragma unroll
;         for (int ai = 0; ai < 2; ++ai)
; #pragma unroll
;             for (int m = 0; m < 4; ++m) {
;                 const int row = u.pm * 256 + ai * 128 + wr * 64 + m * 16 + fr;
;                 const float rs = rsqrtf(ssv[ai][m] * (1.0f / DM) + EPS);
;                 bf16_t* dst = act + ((size_t)((row >> 8) * (DFF / 64) + u.pn * 2 + (wc >> 1)) * 256 + (row & 255)) * 64 + (wc & 1) * 32 + fq * 8;
;                 u32x4 w;
; #pragma unroll
;                 for (int n = 0; n < 2; ++n) {
;                     const f32x4 a = acc[ai][0][m][n] * rs, b = acc[ai][1][m][n] * rs; f32x4 v;
; #pragma unroll
;                     for (int j = 0; j < 4; ++j) v[j] = a[j] * fast_sigmoid(a[j]) * b[j];
;                     if (n == 0) { w.x = cvt_pk_bf16(v[0], v[1]); w.y = cvt_pk_bf16(v[2], v[3]); } else { w.z = cvt_pk_bf16(v[0], v[1]); w.w = cvt_pk_bf16(v[2], v[3]); }
;                 }
;                 *(u32x4*)dst = w;
;             }
	v_add_f32_e32 v37, 1.0, v37
	v_rcp_f32_e32 v37, v37
	v_add_f32_e32 v36, 1.0, v36
	v_rcp_f32_e32 v36, v36
	v_mul_f32_e32 v35, v39, v37
	v_mul_f32_e32 v35, v38, v35
	v_mul_f32_e32 v33, v33, v36
	v_fmamk_f32 v36, v151, 0x3a800000, v149
	v_mul_f32_e32 v37, 0x4b800000, v36
	v_cmp_gt_f32_e32 vcc, s54, v36
	v_mul_f32_e32 v32, v32, v33
	v_cvt_pk_bf16_f32 v42, v32, v35
	v_cvt_pk_bf16_f32 v43, v34, v43
	v_mov_b32_e32 v34, v27
	v_cndmask_b32_e32 v36, v36, v37, vcc
	v_rsq_f32_e32 v36, v36
	v_mov_b32_e32 v35, v31
	global_store_dwordx4 v[48:49], v[40:43], off offset:2048
	v_mul_f32_e32 v32, 0x45800000, v36
	v_cndmask_b32_e32 v32, v36, v32, vcc
	v_pk_mul_f32 v[34:35], v[34:35], v[32:33] op_sel_hi:[1,0]
	s_nop 0
	v_mul_f32_e32 v27, 0xbfb8aa3b, v35
	v_exp_f32_e32 v31, v27
	v_mov_b32_e32 v27, v30
	v_pk_mul_f32 v[26:27], v[26:27], v[32:33] op_sel_hi:[1,0]
	v_add_f32_e32 v31, 1.0, v31
	v_mul_f32_e32 v30, 0xbfb8aa3b, v27
	v_exp_f32_e32 v30, v30
	v_rcp_f32_e32 v33, v31
	v_mov_b32_e32 v31, v29
	v_add_f32_e32 v30, 1.0, v30
	v_rcp_f32_e32 v36, v30
	v_mov_b32_e32 v30, v25
	v_pk_mul_f32 v[30:31], v[30:31], v[32:33] op_sel_hi:[1,0]
	v_mul_f32_e32 v29, v35, v33
	v_mul_f32_e32 v25, 0xbfb8aa3b, v31
	v_exp_f32_e32 v25, v25
	v_mul_f32_e32 v27, v27, v36
	v_mul_f32_e32 v29, v34, v29
	v_mul_f32_e32 v34, v26, v27
	v_add_f32_e32 v25, 1.0, v25
	v_rcp_f32_e32 v33, v25
	v_mov_b32_e32 v25, v28
	v_mov_b32_e32 v27, v23
	v_pk_mul_f32 v[24:25], v[24:25], v[32:33] op_sel_hi:[1,0]
	s_nop 0
	v_mul_f32_e32 v28, 0xbfb8aa3b, v25
	v_exp_f32_e32 v28, v28
	v_mul_f32_e32 v26, v31, v33
	v_mul_f32_e32 v30, v30, v26
	v_add_f32_e32 v26, 1.0, v28
	v_rcp_f32_e32 v28, v26
	v_mov_b32_e32 v26, v19
	v_pk_mul_f32 v[26:27], v[26:27], v[32:33] op_sel_hi:[1,0]
	v_mul_f32_e32 v23, v25, v28
	v_mul_f32_e32 v19, 0xbfb8aa3b, v27
	v_exp_f32_e32 v19, v19
	v_mul_f32_e32 v23, v24, v23
	v_cvt_pk_bf16_f32 v24, v23, v30
	v_cvt_pk_bf16_f32 v25, v34, v29
	v_add_f32_e32 v19, 1.0, v19
	v_rcp_f32_e32 v23, v19
	v_mov_b32_e32 v19, v22
	v_pk_mul_f32 v[18:19], v[18:19], v[32:33] op_sel_hi:[1,0]
	v_mul_f32_e32 v23, v27, v23
	v_mul_f32_e32 v22, 0xbfb8aa3b, v19
	v_exp_f32_e32 v22, v22
	v_mul_f32_e32 v27, v26, v23
	v_mov_b32_e32 v23, v21
	v_add_f32_e32 v22, 1.0, v22
	v_rcp_f32_e32 v26, v22
	v_mov_b32_e32 v22, v17
	v_pk_mul_f32 v[22:23], v[22:23], v[32:33] op_sel_hi:[1,0]
	v_mul_f32_e32 v19, v19, v26
	v_mul_f32_e32 v17, 0xbfb8aa3b, v23
	v_exp_f32_e32 v21, v17
	v_mov_b32_e32 v17, v20
	v_pk_mul_f32 v[16:17], v[16:17], v[32:33] op_sel_hi:[1,0]
	v_mul_f32_e32 v18, v18, v19
	v_mul_f32_e32 v20, 0xbfb8aa3b, v17
	v_exp_f32_e32 v20, v20
	v_add_f32_e32 v21, 1.0, v21
	v_rcp_f32_e32 v21, v21
	v_add_f32_e32 v20, 1.0, v20
	v_rcp_f32_e32 v20, v20
	v_mul_f32_e32 v19, v23, v21
	v_mul_f32_e32 v19, v22, v19
	v_mov_b32_e32 v21, v15
	v_mul_f32_e32 v17, v17, v20
	v_mul_f32_e32 v16, v16, v17
	v_cvt_pk_bf16_f32 v26, v16, v19
	v_fmamk_f32 v16, v150, 0x3a800000, v149
	v_mul_f32_e32 v17, 0x4b800000, v16
	v_cmp_gt_f32_e32 vcc, s54, v16
	v_cvt_pk_bf16_f32 v27, v18, v27
	v_mov_b32_e32 v20, v11
	s_nop 0
	v_cndmask_b32_e32 v16, v16, v17, vcc
	v_rsq_f32_e32 v18, v16
	v_add_co_u32_e64 v16, s[0:1], s55, v48
	v_mul_f32_e32 v19, 0x45800000, v18
	v_cndmask_b32_e32 v18, v18, v19, vcc
	v_pk_mul_f32 v[20:21], v[20:21], v[18:19] op_sel_hi:[1,0]
	v_addc_co_u32_e64 v17, s[0:1], 0, v49, s[0:1]
	v_mul_f32_e32 v11, 0xbfb8aa3b, v21
	v_exp_f32_e32 v15, v11
	v_mov_b32_e32 v11, v14
	v_pk_mul_f32 v[10:11], v[10:11], v[18:19] op_sel_hi:[1,0]
	global_store_dwordx4 v[16:17], v[24:27], off
	v_mul_f32_e32 v14, 0xbfb8aa3b, v11
	v_exp_f32_e32 v14, v14
	v_add_f32_e32 v15, 1.0, v15
	v_rcp_f32_e32 v19, v15
	v_mov_b32_e32 v15, v13
	v_add_f32_e32 v14, 1.0, v14
	v_rcp_f32_e32 v22, v14
	v_mov_b32_e32 v14, v9
	v_pk_mul_f32 v[14:15], v[14:15], v[18:19] op_sel_hi:[1,0]
	v_mul_f32_e32 v13, v21, v19
	v_mul_f32_e32 v9, 0xbfb8aa3b, v15
	v_exp_f32_e32 v9, v9
	v_mul_f32_e32 v11, v11, v22
	v_mul_f32_e32 v13, v20, v13
	v_mul_f32_e32 v20, v10, v11
	v_add_f32_e32 v9, 1.0, v9
	v_rcp_f32_e32 v19, v9
	v_mov_b32_e32 v9, v12
	v_mov_b32_e32 v11, v7
	s_andn2_b64 vcc, exec, s[2:3]
	v_pk_mul_f32 v[8:9], v[8:9], v[18:19] op_sel_hi:[1,0]
	v_mul_f32_e32 v10, v15, v19
	v_mul_f32_e32 v12, 0xbfb8aa3b, v9
	v_exp_f32_e32 v12, v12
	v_mul_f32_e32 v14, v14, v10
	s_mov_b64 s[0:1], -1
	v_add_f32_e32 v10, 1.0, v12
	v_rcp_f32_e32 v12, v10
	v_mov_b32_e32 v10, v3
	v_pk_mul_f32 v[10:11], v[10:11], v[18:19] op_sel_hi:[1,0]
	v_mul_f32_e32 v7, v9, v12
	v_mul_f32_e32 v3, 0xbfb8aa3b, v11
	v_exp_f32_e32 v3, v3
	v_mul_f32_e32 v7, v8, v7
	v_cvt_pk_bf16_f32 v8, v7, v14
	v_cvt_pk_bf16_f32 v9, v20, v13
	v_add_f32_e32 v3, 1.0, v3
	v_rcp_f32_e32 v7, v3
	v_mov_b32_e32 v3, v6
	v_pk_mul_f32 v[2:3], v[2:3], v[18:19] op_sel_hi:[1,0]
	v_mul_f32_e32 v7, v11, v7
	v_mul_f32_e32 v6, 0xbfb8aa3b, v3
	v_exp_f32_e32 v6, v6
	v_mul_f32_e32 v11, v10, v7
	v_mov_b32_e32 v7, v5
	v_add_f32_e32 v6, 1.0, v6
	v_rcp_f32_e32 v10, v6
	v_mov_b32_e32 v6, v1
	v_pk_mul_f32 v[6:7], v[6:7], v[18:19] op_sel_hi:[1,0]
	v_mul_f32_e32 v3, v3, v10
	v_mul_f32_e32 v1, 0xbfb8aa3b, v7
	v_exp_f32_e32 v5, v1
	v_mov_b32_e32 v1, v4
	v_pk_mul_f32 v[0:1], v[0:1], v[18:19] op_sel_hi:[1,0]
	v_mul_f32_e32 v2, v2, v3
	v_mul_f32_e32 v4, 0xbfb8aa3b, v1
	v_exp_f32_e32 v4, v4
	v_add_f32_e32 v5, 1.0, v5
	v_rcp_f32_e32 v5, v5
	v_add_f32_e32 v4, 1.0, v4
	v_rcp_f32_e32 v4, v4
	v_mul_f32_e32 v3, v7, v5
	v_mul_f32_e32 v3, v6, v3
	v_mul_f32_e32 v1, v1, v4
	v_mul_f32_e32 v0, v0, v1
	v_cvt_pk_bf16_f32 v10, v0, v3
	v_cvt_pk_bf16_f32 v11, v2, v11
	global_store_dwordx4 v[16:17], v[8:11], off offset:2048
	s_cbranch_vccnz .LBB0_448
	s_andn2_b64 vcc, exec, s[6:7]
	s_cbranch_vccnz .LBB0_447
	s_barrier
	s_branch .LBB0_447

; #define PG8_WAIT_V(n) asm volatile("s_waitcnt vmcnt(" #n ")" ::: "memory")
; #define PG8_WAIT_L(n) asm volatile("s_waitcnt lgkmcnt(" #n ")" ::: "memory")
; template <class Epi>
; __device__ __forceinline__ void gemm_phase(LAS unsigned char* lds, const Gemm g, const StaticOrder& S, const Epi& E) {
;     ...
;         const bool has_next = S.next(ui + 1, nxt);
;         const char* nA = has_next ? (const char*)g.A + (size_t)nxt.pm * tstepA : cA; const char* nB = has_next ? (const char*)g.Bt + (size_t)nxt.pn * tstepB : cB;
;         for (int t = 0; t < nt; t += 2) {
;             const bool last = (t == nt - 2);
;             const char* a1 = cA + (size_t)(t + 1) * kstepA;
;             const char* a2 = last ? nA : cA + (size_t)(t + 2) * kstepA; const char* b2 = last ? nB : cB + (size_t)(t + 2) * kstep;
;             const char* a3 = a2 + kstepA; const char* b3 = b2 + kstep;
;             PG8_LDB(B0, 0, 0); PG8_LDB(B1, 0, 1); PG8_SCHED; PG8_LDA(At, 0, 0); PG8_STAGE(PG8_SA(1, 1), a1 + hstepA, voffA);
;             PG8_WAIT_V(8); PG8_WAIT_L(0); PG8_BAR; PG8_MMA(0, 0, At, B0); PG8_MMA(0, 1, At, B1); PG8_BAR; PG8_SCHED;
;             PG8_LDA(At, 0, 1); PG8_STAGE(PG8_SB(0, 0), b2, voffB); PG8_STAGE(PG8_SB(0, 1), b2 + hstepB, voffB); PG8_STAGE(PG8_SA(0, 0), a2, voffA);
;             PG8_WAIT_V(8); PG8_WAIT_L(0); PG8_BAR; PG8_MMA(1, 0, At, B0); PG8_MMA(1, 1, At, B1); PG8_BAR; PG8_SCHED;
;             PG8_LDB(B0, 1, 0); PG8_LDB(B1, 1, 1); PG8_SCHED; PG8_LDA(At, 1, 0); PG8_STAGE(PG8_SA(0, 1), a2 + hstepA, voffA);
;             PG8_WAIT_V(8); PG8_WAIT_L(0); PG8_BAR; PG8_MMA(0, 0, At, B0); PG8_MMA(0, 1, At, B1); PG8_BAR; PG8_SCHED;
;             PG8_LDA(At, 1, 1); PG8_STAGE(PG8_SB(1, 0), b3, voffB); PG8_STAGE(PG8_SB(1, 1), b3 + hstepB, voffB); PG8_STAGE(PG8_SA(1, 0), a3, voffA);
;             PG8_WAIT_V(8); PG8_WAIT_L(0); PG8_BAR; PG8_MMA(1, 0, At, B0); PG8_MMA(1, 1, At, B1); PG8_BAR; PG8_SCHED;
;         }
;         if (wr == 0) PG8_BAR;
;         E(acc, cur, wr, wc, fr, fq);
;         if (!has_next) break;
; #pragma unroll
;         for (int a = 0; a < 2; ++a)
; #pragma unroll
;             for (int b = 0; b < 2; ++b)
; #pragma unroll
;                 for (int m = 0; m < 4; ++m)
; #pragma unroll
;                     for (int n = 0; n < 2; ++n) acc[a][b][m][n] = (f32x4){0.f, 0.f, 0.f, 0.f};
;         cur = nxt; cA = nA; cB = nB; ++ui;
.LBB0_1731:
	s_ashr_i32 s21, s20, 31
	s_lshl_b64 s[22:23], s[20:21], 19
	s_add_u32 s22, s18, s22
	s_addc_u32 s23, s19, s23
	s_and_b64 s[24:25], s[6:7], exec
	s_cselect_b32 s21, s23, s27
	s_cselect_b32 s51, s22, s26
	s_ashr_i32 s15, s14, 31
	s_lshl_b64 s[24:25], s[14:15], 19
	v_readlane_b32 s30, v254, 43
	v_readlane_b32 s31, v254, 44
	s_add_u32 s24, s30, s24
	s_addc_u32 s25, s31, s25
	s_and_b64 s[30:31], s[6:7], exec
	s_cselect_b32 s15, s25, s29
	s_cselect_b32 s52, s24, s28
	s_add_u32 s26, s26, 0x40080
	s_addc_u32 s27, s27, 0
	s_add_u32 s53, s28, 0x100
	v_mov_b32_e32 v0, 0
	s_addc_u32 s54, s29, 0
	s_mov_b32 s55, -2
	v_mov_b32_e32 v1, v0
	v_mov_b32_e32 v2, v0
	v_mov_b32_e32 v3, v0
	v_mov_b32_e32 v8, v0
	v_mov_b32_e32 v9, v0
	v_mov_b32_e32 v10, v0
	v_mov_b32_e32 v11, v0
	v_mov_b32_e32 v16, v0
	v_mov_b32_e32 v17, v0
	v_mov_b32_e32 v18, v0
	v_mov_b32_e32 v19, v0
	v_mov_b32_e32 v24, v0
	v_mov_b32_e32 v25, v0
	v_mov_b32_e32 v26, v0
	v_mov_b32_e32 v27, v0
	v_mov_b32_e32 v32, v0
	v_mov_b32_e32 v33, v0
	v_mov_b32_e32 v34, v0
	v_mov_b32_e32 v35, v0
	v_mov_b32_e32 v40, v0
	v_mov_b32_e32 v41, v0
	v_mov_b32_e32 v42, v0
	v_mov_b32_e32 v43, v0
	v_mov_b32_e32 v48, v0
	v_mov_b32_e32 v49, v0
	v_mov_b32_e32 v50, v0
	v_mov_b32_e32 v51, v0
	v_mov_b32_e32 v56, v0
	v_mov_b32_e32 v57, v0
	v_mov_b32_e32 v58, v0
	v_mov_b32_e32 v59, v0
	v_mov_b32_e32 v4, v0
	v_mov_b32_e32 v5, v0
	v_mov_b32_e32 v6, v0
	v_mov_b32_e32 v7, v0
	v_mov_b32_e32 v12, v0
	v_mov_b32_e32 v13, v0
	v_mov_b32_e32 v14, v0
	v_mov_b32_e32 v15, v0
	v_mov_b32_e32 v20, v0
	v_mov_b32_e32 v21, v0
	v_mov_b32_e32 v22, v0
	v_mov_b32_e32 v23, v0
	v_mov_b32_e32 v28, v0
	v_mov_b32_e32 v29, v0
	v_mov_b32_e32 v30, v0
	v_mov_b32_e32 v31, v0
	v_mov_b32_e32 v36, v0
	v_mov_b32_e32 v37, v0
	v_mov_b32_e32 v38, v0
	v_mov_b32_e32 v39, v0
	v_mov_b32_e32 v44, v0
	v_mov_b32_e32 v45, v0
	v_mov_b32_e32 v46, v0
	v_mov_b32_e32 v47, v0
	v_mov_b32_e32 v52, v0
	v_mov_b32_e32 v53, v0
	v_mov_b32_e32 v54, v0
	v_mov_b32_e32 v55, v0
	v_mov_b32_e32 v60, v0
	v_mov_b32_e32 v61, v0
	v_mov_b32_e32 v62, v0
	v_mov_b32_e32 v63, v0
	s_waitcnt vmcnt(0)
	v_mov_b32_e32 v64, v0
	v_mov_b32_e32 v65, v0
	v_mov_b32_e32 v66, v0
	v_mov_b32_e32 v67, v0
	v_mov_b32_e32 v72, v0
	v_mov_b32_e32 v73, v0
	v_mov_b32_e32 v74, v0
	v_mov_b32_e32 v75, v0
	v_mov_b32_e32 v80, v0
	v_mov_b32_e32 v81, v0
	v_mov_b32_e32 v82, v0
	v_mov_b32_e32 v83, v0
	v_mov_b32_e32 v88, v0
	v_mov_b32_e32 v89, v0
	v_mov_b32_e32 v90, v0
	v_mov_b32_e32 v91, v0
	v_mov_b32_e32 v96, v0
	v_mov_b32_e32 v97, v0
	v_mov_b32_e32 v98, v0
	v_mov_b32_e32 v99, v0
	v_mov_b32_e32 v104, v0
	v_mov_b32_e32 v105, v0
	v_mov_b32_e32 v106, v0
	v_mov_b32_e32 v107, v0
	v_mov_b32_e32 v112, v0
	v_mov_b32_e32 v113, v0
	v_mov_b32_e32 v114, v0
	v_mov_b32_e32 v115, v0
	v_mov_b32_e32 v120, v0
	v_mov_b32_e32 v121, v0
	v_mov_b32_e32 v122, v0
	v_mov_b32_e32 v123, v0
	v_mov_b32_e32 v68, v0
	v_mov_b32_e32 v69, v0
	v_mov_b32_e32 v70, v0
	v_mov_b32_e32 v71, v0
	v_mov_b32_e32 v76, v0
	v_mov_b32_e32 v77, v0
	v_mov_b32_e32 v78, v0
	v_mov_b32_e32 v79, v0
	v_mov_b32_e32 v84, v0
	v_mov_b32_e32 v85, v0
	v_mov_b32_e32 v86, v0
	v_mov_b32_e32 v87, v0
	v_mov_b32_e32 v92, v0
	v_mov_b32_e32 v93, v0
	v_mov_b32_e32 v94, v0
	v_mov_b32_e32 v95, v0
	v_mov_b32_e32 v100, v0
	v_mov_b32_e32 v101, v0
	v_mov_b32_e32 v102, v0
	v_mov_b32_e32 v103, v0
	v_mov_b32_e32 v108, v0
	v_mov_b32_e32 v109, v0
	v_mov_b32_e32 v110, v0
	v_mov_b32_e32 v111, v0
	v_mov_b32_e32 v116, v0
	v_mov_b32_e32 v117, v0
	v_mov_b32_e32 v118, v0
	v_mov_b32_e32 v119, v0
	v_mov_b32_e32 v124, v0
	v_mov_b32_e32 v125, v0
	v_mov_b32_e32 v126, v0
	v_mov_b32_e32 v127, v0
	s_lshl_b32 s85, s0, 8
	s_add_i32 s85, s85, s40
	v_or_b32_e32 v250, s85, v144
	v_ashrrev_i32_e32 v251, 31, v250
	v_lshl_add_u64 v[252:253], v[250:251], 2, s[16:17]
	global_load_dword v235, v[252:253], off
	global_load_dword v236, v[252:253], off offset:64
	global_load_dword v237, v[252:253], off offset:128
	global_load_dword v238, v[252:253], off offset:192
	global_load_dword v239, v[252:253], off offset:512
	global_load_dword v240, v[252:253], off offset:576
	global_load_dword v241, v[252:253], off offset:640
	global_load_dword v242, v[252:253], off offset:704

; __device__ __forceinline__ unsigned cvt_pk_bf16(float lo, float hi) { unsigned r; asm volatile("v_cvt_pk_bf16_f32 %0, %1, %2" : "=v"(r) : "v"(lo), "v"(hi)); return r; }
; __device__ __forceinline__ float fast_sigmoid(float a) { return __builtin_amdgcn_rcpf(1.0f + __expf(-a)); }
;     __device__ __forceinline__ void operator()(const Acc& acc, const Unit& u, int wr, int wc, int fr, int fq) const {
;     ...
; #pragma unroll
;         for (int ai = 0; ai < 2; ++ai)
; #pragma unroll
;             for (int m = 0; m < 4; ++m) {
;                 const int row = u.pm * 256 + ai * 128 + wr * 64 + m * 16 + fr;
;                 const float rs = rsqrtf(ssv[ai][m] * (1.0f / DM) + EPS);
;                 bf16_t* dst = act + ((size_t)((row >> 8) * (DFF / 64) + u.pn * 2 + (wc >> 1)) * 256 + (row & 255)) * 64 + (wc & 1) * 32 + fq * 8;
;                 u32x4 w;
; #pragma unroll
;                 for (int n = 0; n < 2; ++n) {
;                     const f32x4 a = acc[ai][0][m][n] * rs, b = acc[ai][1][m][n] * rs; f32x4 v;
; #pragma unroll
;                     for (int j = 0; j < 4; ++j) v[j] = a[j] * fast_sigmoid(a[j]) * b[j];
;                     if (n == 0) { w.x = cvt_pk_bf16(v[0], v[1]); w.y = cvt_pk_bf16(v[2], v[3]); } else { w.z = cvt_pk_bf16(v[0], v[1]); w.w = cvt_pk_bf16(v[2], v[3]); }
;                 }
;                 *(u32x4*)dst = w;
;             }
.LBB0_1735:
	s_lshl_b32 s15, s0, 8
	s_add_i32 s15, s15, s40
	v_or_b32_e32 v150, s15, v144
	v_ashrrev_i32_e32 v151, 31, v150
	v_lshl_add_u64 v[152:153], v[150:151], 2, s[16:17]
	v_add_u32_e32 v154, 0x80, v150
	v_add_u32_e32 v156, 0x90, v150
	v_add_u32_e32 v158, 0xa0, v150
	v_add_u32_e32 v150, 0xb0, v150
	v_ashrrev_i32_e32 v155, 31, v154
	v_ashrrev_i32_e32 v157, 31, v156
	v_ashrrev_i32_e32 v159, 31, v158
	v_ashrrev_i32_e32 v151, 31, v150
	v_lshl_add_u64 v[154:155], v[154:155], 2, s[16:17]
	v_lshl_add_u64 v[156:157], v[156:157], 2, s[16:17]
	v_lshl_add_u64 v[158:159], v[158:159], 2, s[16:17]
	v_lshl_add_u64 v[160:161], v[150:151], 2, s[16:17]
	v_mov_b32_e32 v162, v235
	v_mov_b32_e32 v163, v236
	v_mov_b32_e32 v164, v237
	v_mov_b32_e32 v165, v238
	s_nop 0
	v_mov_b32_e32 v153, v239
	v_mov_b32_e32 v152, v240
	v_mov_b32_e32 v151, v241
	v_mov_b32_e32 v150, v242
	s_nop 0
	v_fmamk_f32 v154, v162, 0x3a800000, v149
	v_mul_f32_e32 v155, 0x4b800000, v154
	v_cmp_gt_f32_e32 vcc, s48, v154
	v_mov_b32_e32 v158, v123
	v_mov_b32_e32 v159, v127
	v_cndmask_b32_e32 v154, v154, v155, vcc
	v_rsq_f32_e32 v154, v154
	s_lshl_b32 s0, s1, 1
	s_or_b32 s21, s0, s43
	s_ashr_i32 s0, s15, 8
	v_mul_f32_e32 v155, 0x45800000, v154
	v_cndmask_b32_e32 v154, v154, v155, vcc
	v_pk_mul_f32 v[158:159], v[158:159], v[154:155] op_sel_hi:[1,0]
	s_mul_i32 s0, s0, 44
	v_mul_f32_e32 v123, 0xbfb8aa3b, v159
	v_exp_f32_e32 v155, v123
	v_mov_b32_e32 v123, v126
	s_add_i32 s0, s0, s21
	s_ashr_i32 s1, s0, 31
	v_pk_mul_f32 v[122:123], v[122:123], v[154:155] op_sel_hi:[1,0]
	v_add_f32_e32 v155, 1.0, v155
	v_mul_f32_e32 v126, 0xbfb8aa3b, v123
	v_exp_f32_e32 v160, v126
	s_lshl_b64 s[0:1], s[0:1], 15
	v_rcp_f32_e32 v155, v155
	v_lshl_add_u64 v[156:157], v[134:135], 0, s[0:1]
	v_lshl_add_u64 v[126:127], v[156:157], 0, s[2:3]
	v_add_f32_e32 v156, 1.0, v160
	v_rcp_f32_e32 v160, v156
	v_mov_b32_e32 v156, v121
	v_mov_b32_e32 v157, v125
	v_pk_mul_f32 v[156:157], v[156:157], v[154:155] op_sel_hi:[1,0]
	v_mul_f32_e32 v125, v159, v155
	v_mul_f32_e32 v121, 0xbfb8aa3b, v157
	v_exp_f32_e32 v121, v121
	v_mul_f32_e32 v123, v123, v160
	v_mul_f32_e32 v125, v158, v125
	v_mul_f32_e32 v158, v122, v123
	v_add_f32_e32 v121, 1.0, v121
	v_rcp_f32_e32 v155, v121
	v_mov_b32_e32 v121, v124
	v_mov_b32_e32 v123, v119
	s_addk_i32 s15, 0x80
	v_pk_mul_f32 v[120:121], v[120:121], v[154:155] op_sel_hi:[1,0]
	v_mul_f32_e32 v122, v157, v155
	v_mul_f32_e32 v124, 0xbfb8aa3b, v121
	v_exp_f32_e32 v124, v124
	v_mul_f32_e32 v155, v156, v122
	v_readlane_b32 s26, v254, 51
	v_readlane_b32 s27, v254, 52
	v_add_f32_e32 v122, 1.0, v124
	v_rcp_f32_e32 v124, v122
	v_mov_b32_e32 v122, v115
	v_pk_mul_f32 v[122:123], v[122:123], v[154:155] op_sel_hi:[1,0]
	v_mul_f32_e32 v119, v121, v124
	v_mul_f32_e32 v115, 0xbfb8aa3b, v123
	v_exp_f32_e32 v115, v115
	v_mul_f32_e32 v119, v120, v119
	v_cvt_pk_bf16_f32 v120, v119, v155
	v_cvt_pk_bf16_f32 v121, v158, v125
	v_add_f32_e32 v115, 1.0, v115
	v_rcp_f32_e32 v119, v115
	v_mov_b32_e32 v115, v118
	v_pk_mul_f32 v[114:115], v[114:115], v[154:155] op_sel_hi:[1,0]
	v_mul_f32_e32 v119, v123, v119
	v_mul_f32_e32 v118, 0xbfb8aa3b, v115
	v_exp_f32_e32 v118, v118
	v_mul_f32_e32 v123, v122, v119
	v_mov_b32_e32 v119, v117
	v_add_f32_e32 v118, 1.0, v118
	v_rcp_f32_e32 v122, v118
	v_mov_b32_e32 v118, v113
	v_pk_mul_f32 v[118:119], v[118:119], v[154:155] op_sel_hi:[1,0]
	v_mul_f32_e32 v115, v115, v122
	v_mul_f32_e32 v113, 0xbfb8aa3b, v119
	v_exp_f32_e32 v117, v113
	v_mov_b32_e32 v113, v116
	v_pk_mul_f32 v[112:113], v[112:113], v[154:155] op_sel_hi:[1,0]
	v_mul_f32_e32 v114, v114, v115
	v_mul_f32_e32 v116, 0xbfb8aa3b, v113
	v_exp_f32_e32 v116, v116
	v_add_f32_e32 v117, 1.0, v117
	v_rcp_f32_e32 v117, v117
	v_add_f32_e32 v116, 1.0, v116
	v_rcp_f32_e32 v116, v116
	v_mul_f32_e32 v115, v119, v117
	v_mul_f32_e32 v115, v118, v115
	v_mov_b32_e32 v117, v111
	v_mul_f32_e32 v113, v113, v116
	v_mul_f32_e32 v112, v112, v113
	v_fmamk_f32 v113, v163, 0x3a800000, v149
	v_mul_f32_e32 v116, 0x4b800000, v113
	v_cmp_gt_f32_e32 vcc, s48, v113
	v_cvt_pk_bf16_f32 v122, v112, v115
	v_cvt_pk_bf16_f32 v123, v114, v123
	s_nop 1
	v_cndmask_b32_e32 v113, v113, v116, vcc
	v_rsq_f32_e32 v116, v113
	v_lshl_add_u64 v[112:113], v[126:127], 0, v[132:133]
	global_store_dwordx4 v[112:113], v[120:123], off
	v_mul_f32_e32 v114, 0x45800000, v116
	v_cndmask_b32_e32 v114, v116, v114, vcc
	v_mov_b32_e32 v116, v107
	v_pk_mul_f32 v[116:117], v[116:117], v[114:115] op_sel_hi:[1,0]
	s_nop 0
	v_mul_f32_e32 v107, 0xbfb8aa3b, v117
	v_exp_f32_e32 v111, v107
	v_mov_b32_e32 v107, v110
	v_pk_mul_f32 v[106:107], v[106:107], v[114:115] op_sel_hi:[1,0]
	v_add_f32_e32 v111, 1.0, v111
	v_mul_f32_e32 v110, 0xbfb8aa3b, v107
	v_exp_f32_e32 v110, v110
	v_rcp_f32_e32 v115, v111
	v_mov_b32_e32 v111, v109
	v_add_f32_e32 v110, 1.0, v110
	v_rcp_f32_e32 v118, v110
	v_mov_b32_e32 v110, v105
	v_pk_mul_f32 v[110:111], v[110:111], v[114:115] op_sel_hi:[1,0]
	v_mul_f32_e32 v109, v117, v115
	v_mul_f32_e32 v105, 0xbfb8aa3b, v111
	v_exp_f32_e32 v105, v105
	v_mul_f32_e32 v107, v107, v118
	v_mul_f32_e32 v109, v116, v109
	v_mul_f32_e32 v116, v106, v107
	v_add_f32_e32 v105, 1.0, v105
	v_rcp_f32_e32 v115, v105
	v_mov_b32_e32 v105, v108
	v_mov_b32_e32 v107, v103
	v_pk_mul_f32 v[104:105], v[104:105], v[114:115] op_sel_hi:[1,0]
	s_nop 0
	v_mul_f32_e32 v108, 0xbfb8aa3b, v105
	v_exp_f32_e32 v108, v108
	v_mul_f32_e32 v106, v111, v115
	v_mul_f32_e32 v110, v110, v106
	v_add_f32_e32 v106, 1.0, v108
	v_rcp_f32_e32 v108, v106
	v_mov_b32_e32 v106, v99
	v_pk_mul_f32 v[106:107], v[106:107], v[114:115] op_sel_hi:[1,0]
	v_mul_f32_e32 v103, v105, v108
	v_mul_f32_e32 v99, 0xbfb8aa3b, v107
	v_exp_f32_e32 v99, v99
; __device__ __forceinline__ unsigned cvt_pk_bf16(float lo, float hi) { unsigned r; asm volatile("v_cvt_pk_bf16_f32 %0, %1, %2" : "=v"(r) : "v"(lo), "v"(hi)); return r; }
; __device__ __forceinline__ float fast_sigmoid(float a) { return __builtin_amdgcn_rcpf(1.0f + __expf(-a)); }
;     __device__ __forceinline__ void operator()(const Acc& acc, const Unit& u, int wr, int wc, int fr, int fq) const {
;     ...
; #pragma unroll
;         for (int ai = 0; ai < 2; ++ai)
; #pragma unroll
;             for (int m = 0; m < 4; ++m) {
;                 const int row = u.pm * 256 + ai * 128 + wr * 64 + m * 16 + fr;
;                 const float rs = rsqrtf(ssv[ai][m] * (1.0f / DM) + EPS);
;                 bf16_t* dst = act + ((size_t)((row >> 8) * (DFF / 64) + u.pn * 2 + (wc >> 1)) * 256 + (row & 255)) * 64 + (wc & 1) * 32 + fq * 8;
;                 u32x4 w;
; #pragma unroll
;                 for (int n = 0; n < 2; ++n) {
;                     const f32x4 a = acc[ai][0][m][n] * rs, b = acc[ai][1][m][n] * rs; f32x4 v;
; #pragma unroll
;                     for (int j = 0; j < 4; ++j) v[j] = a[j] * fast_sigmoid(a[j]) * b[j];
;                     if (n == 0) { w.x = cvt_pk_bf16(v[0], v[1]); w.y = cvt_pk_bf16(v[2], v[3]); } else { w.z = cvt_pk_bf16(v[0], v[1]); w.w = cvt_pk_bf16(v[2], v[3]); }
;                 }
;                 *(u32x4*)dst = w;
;             }
	v_mul_f32_e32 v103, v104, v103
	v_cvt_pk_bf16_f32 v104, v103, v110
	v_cvt_pk_bf16_f32 v105, v116, v109
	v_add_f32_e32 v99, 1.0, v99
	v_rcp_f32_e32 v103, v99
	v_mov_b32_e32 v99, v102
	v_pk_mul_f32 v[98:99], v[98:99], v[114:115] op_sel_hi:[1,0]
	v_mul_f32_e32 v103, v107, v103
	v_mul_f32_e32 v102, 0xbfb8aa3b, v99
	v_exp_f32_e32 v102, v102
	v_mul_f32_e32 v107, v106, v103
	v_mov_b32_e32 v103, v101
	v_add_f32_e32 v102, 1.0, v102
	v_rcp_f32_e32 v106, v102
	v_mov_b32_e32 v102, v97
	v_pk_mul_f32 v[102:103], v[102:103], v[114:115] op_sel_hi:[1,0]
	v_mul_f32_e32 v99, v99, v106
	v_mul_f32_e32 v97, 0xbfb8aa3b, v103
	v_exp_f32_e32 v101, v97
	v_mov_b32_e32 v97, v100
	v_pk_mul_f32 v[96:97], v[96:97], v[114:115] op_sel_hi:[1,0]
	v_mul_f32_e32 v98, v98, v99
	v_mul_f32_e32 v100, 0xbfb8aa3b, v97
	v_exp_f32_e32 v100, v100
	v_add_f32_e32 v101, 1.0, v101
	v_rcp_f32_e32 v101, v101
	v_add_f32_e32 v100, 1.0, v100
	v_rcp_f32_e32 v100, v100
	v_mul_f32_e32 v99, v103, v101
	v_mul_f32_e32 v99, v102, v99
	v_mul_f32_e32 v97, v97, v100
	v_fmamk_f32 v100, v164, 0x3a800000, v149
	v_mul_f32_e32 v101, 0x4b800000, v100
	v_cmp_gt_f32_e32 vcc, s48, v100
	v_mul_f32_e32 v96, v96, v97
	v_cvt_pk_bf16_f32 v106, v96, v99
	v_cvt_pk_bf16_f32 v107, v98, v107
	v_mov_b32_e32 v98, v91
	v_cndmask_b32_e32 v100, v100, v101, vcc
	v_rsq_f32_e32 v100, v100
	v_mov_b32_e32 v99, v95
	global_store_dwordx4 v[112:113], v[104:107], off offset:2048
	v_mul_f32_e32 v96, 0x45800000, v100
	v_cndmask_b32_e32 v96, v100, v96, vcc
	v_pk_mul_f32 v[98:99], v[98:99], v[96:97] op_sel_hi:[1,0]
	s_nop 0
	v_mul_f32_e32 v91, 0xbfb8aa3b, v99
	v_exp_f32_e32 v95, v91
	v_mov_b32_e32 v91, v94
	v_pk_mul_f32 v[90:91], v[90:91], v[96:97] op_sel_hi:[1,0]
	v_add_f32_e32 v95, 1.0, v95
	v_mul_f32_e32 v94, 0xbfb8aa3b, v91
	v_exp_f32_e32 v94, v94
	v_rcp_f32_e32 v97, v95
	v_mov_b32_e32 v95, v93
	v_add_f32_e32 v94, 1.0, v94
	v_rcp_f32_e32 v100, v94
	v_mov_b32_e32 v94, v89
	v_pk_mul_f32 v[94:95], v[94:95], v[96:97] op_sel_hi:[1,0]
	v_mul_f32_e32 v93, v99, v97
	v_mul_f32_e32 v89, 0xbfb8aa3b, v95
	v_exp_f32_e32 v89, v89
	v_mul_f32_e32 v91, v91, v100
	v_mul_f32_e32 v93, v98, v93
	v_mul_f32_e32 v98, v90, v91
	v_add_f32_e32 v89, 1.0, v89
	v_rcp_f32_e32 v97, v89
	v_mov_b32_e32 v89, v92
	v_mov_b32_e32 v91, v87
	v_pk_mul_f32 v[88:89], v[88:89], v[96:97] op_sel_hi:[1,0]
	s_nop 0
	v_mul_f32_e32 v92, 0xbfb8aa3b, v89
	v_exp_f32_e32 v92, v92
	v_mul_f32_e32 v90, v95, v97
	v_mul_f32_e32 v94, v94, v90
	v_add_f32_e32 v90, 1.0, v92
	v_rcp_f32_e32 v92, v90
	v_mov_b32_e32 v90, v83
	v_pk_mul_f32 v[90:91], v[90:91], v[96:97] op_sel_hi:[1,0]
	v_mul_f32_e32 v87, v89, v92
	v_mul_f32_e32 v83, 0xbfb8aa3b, v91
	v_exp_f32_e32 v83, v83
	v_mul_f32_e32 v87, v88, v87
	v_cvt_pk_bf16_f32 v88, v87, v94
	v_cvt_pk_bf16_f32 v89, v98, v93
	v_add_f32_e32 v83, 1.0, v83
	v_rcp_f32_e32 v87, v83
	v_mov_b32_e32 v83, v86
	v_pk_mul_f32 v[82:83], v[82:83], v[96:97] op_sel_hi:[1,0]
	v_mul_f32_e32 v87, v91, v87
	v_mul_f32_e32 v86, 0xbfb8aa3b, v83
	v_exp_f32_e32 v86, v86
	v_mul_f32_e32 v91, v90, v87
	v_mov_b32_e32 v87, v85
	v_add_f32_e32 v86, 1.0, v86
	v_rcp_f32_e32 v90, v86
	v_mov_b32_e32 v86, v81
	v_pk_mul_f32 v[86:87], v[86:87], v[96:97] op_sel_hi:[1,0]
	v_mul_f32_e32 v83, v83, v90
	v_mul_f32_e32 v81, 0xbfb8aa3b, v87
	v_exp_f32_e32 v85, v81
	v_mov_b32_e32 v81, v84
	v_pk_mul_f32 v[80:81], v[80:81], v[96:97] op_sel_hi:[1,0]
	v_mul_f32_e32 v82, v82, v83
	v_mul_f32_e32 v84, 0xbfb8aa3b, v81
	v_exp_f32_e32 v84, v84
	v_add_f32_e32 v85, 1.0, v85
	v_rcp_f32_e32 v85, v85
	v_add_f32_e32 v84, 1.0, v84
	v_rcp_f32_e32 v84, v84
	v_mul_f32_e32 v83, v87, v85
	v_mul_f32_e32 v83, v86, v83
	v_mov_b32_e32 v85, v79
	v_mul_f32_e32 v81, v81, v84
	v_mul_f32_e32 v80, v80, v81
	v_cvt_pk_bf16_f32 v90, v80, v83
	v_fmamk_f32 v80, v165, 0x3a800000, v149
	v_mul_f32_e32 v81, 0x4b800000, v80
	v_cmp_gt_f32_e32 vcc, s48, v80
	v_cvt_pk_bf16_f32 v91, v82, v91
	v_mov_b32_e32 v84, v75
	s_nop 0
	v_cndmask_b32_e32 v80, v80, v81, vcc
	v_rsq_f32_e32 v82, v80
	v_add_co_u32_e64 v80, s[0:1], s49, v112
	v_mul_f32_e32 v83, 0x45800000, v82
	v_cndmask_b32_e32 v82, v82, v83, vcc
	v_pk_mul_f32 v[84:85], v[84:85], v[82:83] op_sel_hi:[1,0]
	v_addc_co_u32_e64 v81, s[0:1], 0, v113, s[0:1]
	v_mul_f32_e32 v75, 0xbfb8aa3b, v85
	v_exp_f32_e32 v79, v75
	v_mov_b32_e32 v75, v78
	v_pk_mul_f32 v[74:75], v[74:75], v[82:83] op_sel_hi:[1,0]
	global_store_dwordx4 v[80:81], v[88:91], off
	v_mul_f32_e32 v78, 0xbfb8aa3b, v75
	v_exp_f32_e32 v78, v78
	v_add_f32_e32 v79, 1.0, v79
	v_rcp_f32_e32 v83, v79
	v_mov_b32_e32 v79, v77
	v_add_f32_e32 v78, 1.0, v78
	v_rcp_f32_e32 v86, v78
	v_mov_b32_e32 v78, v73
	v_pk_mul_f32 v[78:79], v[78:79], v[82:83] op_sel_hi:[1,0]
	v_mul_f32_e32 v77, v85, v83
	v_mul_f32_e32 v73, 0xbfb8aa3b, v79
	v_exp_f32_e32 v73, v73
	v_mul_f32_e32 v75, v75, v86
	v_mul_f32_e32 v77, v84, v77
	v_mul_f32_e32 v84, v74, v75
	v_add_f32_e32 v73, 1.0, v73
	v_rcp_f32_e32 v83, v73
	v_mov_b32_e32 v73, v76
	v_mov_b32_e32 v75, v71
	s_ashr_i32 s0, s15, 8
	v_pk_mul_f32 v[72:73], v[72:73], v[82:83] op_sel_hi:[1,0]
	v_mul_f32_e32 v74, v79, v83
	v_mul_f32_e32 v76, 0xbfb8aa3b, v73
	v_exp_f32_e32 v76, v76
	v_mul_f32_e32 v78, v78, v74
	s_and_b32 s15, s15, 0xc0
	s_mul_i32 s0, s0, 44
	v_add_f32_e32 v74, 1.0, v76
	v_rcp_f32_e32 v76, v74
	v_mov_b32_e32 v74, v67
	v_pk_mul_f32 v[74:75], v[74:75], v[82:83] op_sel_hi:[1,0]
	s_add_i32 s0, s0, s21
	v_mul_f32_e32 v67, 0xbfb8aa3b, v75
	v_exp_f32_e32 v67, v67
	v_mul_f32_e32 v71, v73, v76
	v_mul_f32_e32 v71, v72, v71
	v_cvt_pk_bf16_f32 v72, v71, v78
	v_add_f32_e32 v67, 1.0, v67
	v_rcp_f32_e32 v71, v67
	v_mov_b32_e32 v67, v70
	v_pk_mul_f32 v[66:67], v[66:67], v[82:83] op_sel_hi:[1,0]
	v_cvt_pk_bf16_f32 v73, v84, v77
; __device__ __forceinline__ unsigned cvt_pk_bf16(float lo, float hi) { unsigned r; asm volatile("v_cvt_pk_bf16_f32 %0, %1, %2" : "=v"(r) : "v"(lo), "v"(hi)); return r; }
; __device__ __forceinline__ float fast_sigmoid(float a) { return __builtin_amdgcn_rcpf(1.0f + __expf(-a)); }
;     __device__ __forceinline__ void operator()(const Acc& acc, const Unit& u, int wr, int wc, int fr, int fq) const {
;     ...
; #pragma unroll
;         for (int ai = 0; ai < 2; ++ai)
; #pragma unroll
;             for (int m = 0; m < 4; ++m) {
;                 const int row = u.pm * 256 + ai * 128 + wr * 64 + m * 16 + fr;
;                 const float rs = rsqrtf(ssv[ai][m] * (1.0f / DM) + EPS);
;                 bf16_t* dst = act + ((size_t)((row >> 8) * (DFF / 64) + u.pn * 2 + (wc >> 1)) * 256 + (row & 255)) * 64 + (wc & 1) * 32 + fq * 8;
;                 u32x4 w;
; #pragma unroll
;                 for (int n = 0; n < 2; ++n) {
;                     const f32x4 a = acc[ai][0][m][n] * rs, b = acc[ai][1][m][n] * rs; f32x4 v;
; #pragma unroll
;                     for (int j = 0; j < 4; ++j) v[j] = a[j] * fast_sigmoid(a[j]) * b[j];
;                     if (n == 0) { w.x = cvt_pk_bf16(v[0], v[1]); w.y = cvt_pk_bf16(v[2], v[3]); } else { w.z = cvt_pk_bf16(v[0], v[1]); w.w = cvt_pk_bf16(v[2], v[3]); }
;                 }
;                 *(u32x4*)dst = w;
;             }
	v_mul_f32_e32 v71, v75, v71
	v_mul_f32_e32 v70, 0xbfb8aa3b, v67
	v_exp_f32_e32 v70, v70
	v_mul_f32_e32 v75, v74, v71
	v_mov_b32_e32 v71, v69
	s_ashr_i32 s1, s0, 31
	v_add_f32_e32 v70, 1.0, v70
	v_rcp_f32_e32 v74, v70
	v_mov_b32_e32 v70, v65
	v_pk_mul_f32 v[70:71], v[70:71], v[82:83] op_sel_hi:[1,0]
	s_lshl_b64 s[0:1], s[0:1], 15
	v_mul_f32_e32 v65, 0xbfb8aa3b, v71
	v_exp_f32_e32 v69, v65
	v_mov_b32_e32 v65, v68
	v_pk_mul_f32 v[64:65], v[64:65], v[82:83] op_sel_hi:[1,0]
	v_mul_f32_e32 v67, v67, v74
	v_mul_f32_e32 v68, 0xbfb8aa3b, v65
	v_exp_f32_e32 v68, v68
	v_add_f32_e32 v69, 1.0, v69
	v_rcp_f32_e32 v69, v69
	v_mul_f32_e32 v66, v66, v67
	v_add_f32_e32 v68, 1.0, v68
	v_rcp_f32_e32 v68, v68
	v_mul_f32_e32 v67, v71, v69
	v_mul_f32_e32 v67, v70, v67
	v_mov_b32_e32 v69, v63
	v_mul_f32_e32 v65, v65, v68
	v_mul_f32_e32 v64, v64, v65
	v_cvt_pk_bf16_f32 v74, v64, v67
	v_fmamk_f32 v64, v153, 0x3a800000, v149
	v_mul_f32_e32 v65, 0x4b800000, v64
	v_cmp_gt_f32_e32 vcc, s48, v64
	v_cvt_pk_bf16_f32 v75, v66, v75
	v_mov_b32_e32 v68, v59
	s_add_u32 s0, s26, s0
	v_cndmask_b32_e32 v64, v64, v65, vcc
	v_rsq_f32_e32 v64, v64
	v_or_b32_e32 v65, s15, v144
	s_addc_u32 s1, s27, s1
	v_mov_b32_e32 v67, v133
	v_mul_f32_e32 v66, 0x45800000, v64
	v_cndmask_b32_e32 v64, v64, v66, vcc
	v_pk_mul_f32 v[68:69], v[68:69], v[64:65] op_sel_hi:[1,0]
	v_lshlrev_b32_e32 v66, 7, v65
	v_mul_f32_e32 v59, 0xbfb8aa3b, v69
	v_exp_f32_e32 v65, v59
	v_mov_b32_e32 v59, v62
	v_lshl_add_u64 v[66:67], s[0:1], 0, v[66:67]
	global_store_dwordx4 v[80:81], v[72:75], off offset:2048
	v_pk_mul_f32 v[58:59], v[58:59], v[64:65] op_sel_hi:[1,0]
	v_add_f32_e32 v65, 1.0, v65
	v_mul_f32_e32 v62, 0xbfb8aa3b, v59
	v_exp_f32_e32 v70, v62
	v_rcp_f32_e32 v65, v65
	v_lshl_add_u64 v[62:63], v[66:67], 0, s[2:3]
	v_mov_b32_e32 v67, v61
	v_add_f32_e32 v66, 1.0, v70
	v_rcp_f32_e32 v70, v66
	v_mov_b32_e32 v66, v57
	v_pk_mul_f32 v[66:67], v[66:67], v[64:65] op_sel_hi:[1,0]
	v_mul_f32_e32 v61, v69, v65
	v_mul_f32_e32 v57, 0xbfb8aa3b, v67
	v_exp_f32_e32 v57, v57
	v_mul_f32_e32 v59, v59, v70
	v_mul_f32_e32 v61, v68, v61
	v_mul_f32_e32 v68, v58, v59
	v_add_f32_e32 v57, 1.0, v57
	v_rcp_f32_e32 v65, v57
	v_mov_b32_e32 v57, v60
	v_mov_b32_e32 v59, v55
	v_pk_mul_f32 v[56:57], v[56:57], v[64:65] op_sel_hi:[1,0]
	s_nop 0
	v_mul_f32_e32 v60, 0xbfb8aa3b, v57
	v_exp_f32_e32 v60, v60
	v_mul_f32_e32 v58, v67, v65
	v_mul_f32_e32 v65, v66, v58
	v_add_f32_e32 v58, 1.0, v60
	v_rcp_f32_e32 v60, v58
	v_mov_b32_e32 v58, v51
	v_pk_mul_f32 v[58:59], v[58:59], v[64:65] op_sel_hi:[1,0]
	v_mul_f32_e32 v55, v57, v60
	v_mul_f32_e32 v51, 0xbfb8aa3b, v59
	v_exp_f32_e32 v51, v51
	v_mul_f32_e32 v55, v56, v55
	v_cvt_pk_bf16_f32 v56, v55, v65
	v_cvt_pk_bf16_f32 v57, v68, v61
	v_add_f32_e32 v51, 1.0, v51
	v_rcp_f32_e32 v55, v51
	v_mov_b32_e32 v51, v54
	v_pk_mul_f32 v[50:51], v[50:51], v[64:65] op_sel_hi:[1,0]
	v_mul_f32_e32 v55, v59, v55
	v_mul_f32_e32 v54, 0xbfb8aa3b, v51
	v_exp_f32_e32 v54, v54
	v_mul_f32_e32 v59, v58, v55
	v_mov_b32_e32 v55, v53
	v_add_f32_e32 v54, 1.0, v54
	v_rcp_f32_e32 v58, v54
	v_mov_b32_e32 v54, v49
	v_pk_mul_f32 v[54:55], v[54:55], v[64:65] op_sel_hi:[1,0]
	v_mul_f32_e32 v51, v51, v58
	v_mul_f32_e32 v49, 0xbfb8aa3b, v55
	v_exp_f32_e32 v53, v49
	v_mov_b32_e32 v49, v52
	v_pk_mul_f32 v[48:49], v[48:49], v[64:65] op_sel_hi:[1,0]
	v_mul_f32_e32 v50, v50, v51
	v_mul_f32_e32 v52, 0xbfb8aa3b, v49
	v_exp_f32_e32 v52, v52
	v_add_f32_e32 v53, 1.0, v53
	v_rcp_f32_e32 v53, v53
	v_add_f32_e32 v52, 1.0, v52
	v_rcp_f32_e32 v52, v52
	v_mul_f32_e32 v51, v55, v53
	v_mul_f32_e32 v51, v54, v51
	v_mov_b32_e32 v53, v47
	v_mul_f32_e32 v49, v49, v52
	v_mul_f32_e32 v48, v48, v49
	v_fmamk_f32 v49, v152, 0x3a800000, v149
	v_mul_f32_e32 v52, 0x4b800000, v49
	v_cmp_gt_f32_e32 vcc, s48, v49
	v_cvt_pk_bf16_f32 v58, v48, v51
	v_cvt_pk_bf16_f32 v59, v50, v59
	s_nop 1
	v_cndmask_b32_e32 v49, v49, v52, vcc
	v_rsq_f32_e32 v52, v49
	v_lshl_add_u64 v[48:49], v[62:63], 0, v[132:133]
	global_store_dwordx4 v[48:49], v[56:59], off
	v_mul_f32_e32 v50, 0x45800000, v52
	v_cndmask_b32_e32 v50, v52, v50, vcc
	v_mov_b32_e32 v52, v43
	v_pk_mul_f32 v[52:53], v[52:53], v[50:51] op_sel_hi:[1,0]
	s_nop 0
	v_mul_f32_e32 v43, 0xbfb8aa3b, v53
	v_exp_f32_e32 v47, v43
	v_mov_b32_e32 v43, v46
	v_pk_mul_f32 v[42:43], v[42:43], v[50:51] op_sel_hi:[1,0]
	v_add_f32_e32 v47, 1.0, v47
	v_mul_f32_e32 v46, 0xbfb8aa3b, v43
	v_exp_f32_e32 v46, v46
	v_rcp_f32_e32 v51, v47
	v_mov_b32_e32 v47, v45
	v_add_f32_e32 v46, 1.0, v46
	v_rcp_f32_e32 v54, v46
	v_mov_b32_e32 v46, v41
	v_pk_mul_f32 v[46:47], v[46:47], v[50:51] op_sel_hi:[1,0]
	v_mul_f32_e32 v45, v53, v51
	v_mul_f32_e32 v41, 0xbfb8aa3b, v47
	v_exp_f32_e32 v41, v41
	v_mul_f32_e32 v43, v43, v54
	v_mul_f32_e32 v45, v52, v45
	v_mul_f32_e32 v52, v42, v43
	v_add_f32_e32 v41, 1.0, v41
	v_rcp_f32_e32 v51, v41
	v_mov_b32_e32 v41, v44
	v_mov_b32_e32 v43, v39
	v_pk_mul_f32 v[40:41], v[40:41], v[50:51] op_sel_hi:[1,0]
	s_nop 0
	v_mul_f32_e32 v44, 0xbfb8aa3b, v41
	v_exp_f32_e32 v44, v44
	v_mul_f32_e32 v42, v47, v51
	v_mul_f32_e32 v46, v46, v42
	v_add_f32_e32 v42, 1.0, v44
	v_rcp_f32_e32 v44, v42
	v_mov_b32_e32 v42, v35
	v_pk_mul_f32 v[42:43], v[42:43], v[50:51] op_sel_hi:[1,0]
	v_mul_f32_e32 v39, v41, v44
	v_mul_f32_e32 v35, 0xbfb8aa3b, v43
	v_exp_f32_e32 v35, v35
	v_mul_f32_e32 v39, v40, v39
	v_cvt_pk_bf16_f32 v40, v39, v46
	v_cvt_pk_bf16_f32 v41, v52, v45
	v_add_f32_e32 v35, 1.0, v35
	v_rcp_f32_e32 v39, v35
	v_mov_b32_e32 v35, v38
	v_pk_mul_f32 v[34:35], v[34:35], v[50:51] op_sel_hi:[1,0]
	v_mul_f32_e32 v39, v43, v39
	v_mul_f32_e32 v38, 0xbfb8aa3b, v35
	v_exp_f32_e32 v38, v38
	v_mul_f32_e32 v43, v42, v39
	v_mov_b32_e32 v39, v37
	v_add_f32_e32 v38, 1.0, v38
; __device__ __forceinline__ unsigned cvt_pk_bf16(float lo, float hi) { unsigned r; asm volatile("v_cvt_pk_bf16_f32 %0, %1, %2" : "=v"(r) : "v"(lo), "v"(hi)); return r; }
; __device__ __forceinline__ float fast_sigmoid(float a) { return __builtin_amdgcn_rcpf(1.0f + __expf(-a)); }
;     __device__ __forceinline__ void operator()(const Acc& acc, const Unit& u, int wr, int wc, int fr, int fq) const {
;     ...
; #pragma unroll
;         for (int ai = 0; ai < 2; ++ai)
; #pragma unroll
;             for (int m = 0; m < 4; ++m) {
;                 const int row = u.pm * 256 + ai * 128 + wr * 64 + m * 16 + fr;
;                 const float rs = rsqrtf(ssv[ai][m] * (1.0f / DM) + EPS);
;                 bf16_t* dst = act + ((size_t)((row >> 8) * (DFF / 64) + u.pn * 2 + (wc >> 1)) * 256 + (row & 255)) * 64 + (wc & 1) * 32 + fq * 8;
;                 u32x4 w;
; #pragma unroll
;                 for (int n = 0; n < 2; ++n) {
;                     const f32x4 a = acc[ai][0][m][n] * rs, b = acc[ai][1][m][n] * rs; f32x4 v;
; #pragma unroll
;                     for (int j = 0; j < 4; ++j) v[j] = a[j] * fast_sigmoid(a[j]) * b[j];
;                     if (n == 0) { w.x = cvt_pk_bf16(v[0], v[1]); w.y = cvt_pk_bf16(v[2], v[3]); } else { w.z = cvt_pk_bf16(v[0], v[1]); w.w = cvt_pk_bf16(v[2], v[3]); }
;                 }
;                 *(u32x4*)dst = w;
;             }
	v_rcp_f32_e32 v42, v38
	v_mov_b32_e32 v38, v33
	v_pk_mul_f32 v[38:39], v[38:39], v[50:51] op_sel_hi:[1,0]
	v_mul_f32_e32 v35, v35, v42
	v_mul_f32_e32 v33, 0xbfb8aa3b, v39
	v_exp_f32_e32 v37, v33
	v_mov_b32_e32 v33, v36
	v_pk_mul_f32 v[32:33], v[32:33], v[50:51] op_sel_hi:[1,0]
	v_mul_f32_e32 v34, v34, v35
	v_mul_f32_e32 v36, 0xbfb8aa3b, v33
	v_exp_f32_e32 v36, v36
	v_add_f32_e32 v37, 1.0, v37
	v_rcp_f32_e32 v37, v37
	v_add_f32_e32 v36, 1.0, v36
	v_rcp_f32_e32 v36, v36
	v_mul_f32_e32 v35, v39, v37
	v_mul_f32_e32 v35, v38, v35
	v_mul_f32_e32 v33, v33, v36
	v_fmamk_f32 v36, v151, 0x3a800000, v149
	v_mul_f32_e32 v37, 0x4b800000, v36
	v_cmp_gt_f32_e32 vcc, s48, v36
	v_mul_f32_e32 v32, v32, v33
	v_cvt_pk_bf16_f32 v42, v32, v35
	v_cvt_pk_bf16_f32 v43, v34, v43
	v_mov_b32_e32 v34, v27
	v_cndmask_b32_e32 v36, v36, v37, vcc
	v_rsq_f32_e32 v36, v36
	v_mov_b32_e32 v35, v31
	global_store_dwordx4 v[48:49], v[40:43], off offset:2048
	v_mul_f32_e32 v32, 0x45800000, v36
	v_cndmask_b32_e32 v32, v36, v32, vcc
	v_pk_mul_f32 v[34:35], v[34:35], v[32:33] op_sel_hi:[1,0]
	s_nop 0
	v_mul_f32_e32 v27, 0xbfb8aa3b, v35
	v_exp_f32_e32 v31, v27
	v_mov_b32_e32 v27, v30
	v_pk_mul_f32 v[26:27], v[26:27], v[32:33] op_sel_hi:[1,0]
	v_add_f32_e32 v31, 1.0, v31
	v_mul_f32_e32 v30, 0xbfb8aa3b, v27
	v_exp_f32_e32 v30, v30
	v_rcp_f32_e32 v33, v31
	v_mov_b32_e32 v31, v29
	v_add_f32_e32 v30, 1.0, v30
	v_rcp_f32_e32 v36, v30
	v_mov_b32_e32 v30, v25
	v_pk_mul_f32 v[30:31], v[30:31], v[32:33] op_sel_hi:[1,0]
	v_mul_f32_e32 v29, v35, v33
	v_mul_f32_e32 v25, 0xbfb8aa3b, v31
	v_exp_f32_e32 v25, v25
	v_mul_f32_e32 v27, v27, v36
	v_mul_f32_e32 v29, v34, v29
	v_mul_f32_e32 v34, v26, v27
	v_add_f32_e32 v25, 1.0, v25
	v_rcp_f32_e32 v33, v25
	v_mov_b32_e32 v25, v28
	v_mov_b32_e32 v27, v23
	v_pk_mul_f32 v[24:25], v[24:25], v[32:33] op_sel_hi:[1,0]
	s_nop 0
	v_mul_f32_e32 v28, 0xbfb8aa3b, v25
	v_exp_f32_e32 v28, v28
	v_mul_f32_e32 v26, v31, v33
	v_mul_f32_e32 v30, v30, v26
	v_add_f32_e32 v26, 1.0, v28
	v_rcp_f32_e32 v28, v26
	v_mov_b32_e32 v26, v19
	v_pk_mul_f32 v[26:27], v[26:27], v[32:33] op_sel_hi:[1,0]
	v_mul_f32_e32 v23, v25, v28
	v_mul_f32_e32 v19, 0xbfb8aa3b, v27
	v_exp_f32_e32 v19, v19
	v_mul_f32_e32 v23, v24, v23
	v_cvt_pk_bf16_f32 v24, v23, v30
	v_cvt_pk_bf16_f32 v25, v34, v29
	v_add_f32_e32 v19, 1.0, v19
	v_rcp_f32_e32 v23, v19
	v_mov_b32_e32 v19, v22
	v_pk_mul_f32 v[18:19], v[18:19], v[32:33] op_sel_hi:[1,0]
	v_mul_f32_e32 v23, v27, v23
	v_mul_f32_e32 v22, 0xbfb8aa3b, v19
	v_exp_f32_e32 v22, v22
	v_mul_f32_e32 v27, v26, v23
	v_mov_b32_e32 v23, v21
	v_add_f32_e32 v22, 1.0, v22
	v_rcp_f32_e32 v26, v22
	v_mov_b32_e32 v22, v17
	v_pk_mul_f32 v[22:23], v[22:23], v[32:33] op_sel_hi:[1,0]
	v_mul_f32_e32 v19, v19, v26
	v_mul_f32_e32 v17, 0xbfb8aa3b, v23
	v_exp_f32_e32 v21, v17
	v_mov_b32_e32 v17, v20
	v_pk_mul_f32 v[16:17], v[16:17], v[32:33] op_sel_hi:[1,0]
	v_mul_f32_e32 v18, v18, v19
	v_mul_f32_e32 v20, 0xbfb8aa3b, v17
	v_exp_f32_e32 v20, v20
	v_add_f32_e32 v21, 1.0, v21
	v_rcp_f32_e32 v21, v21
	v_add_f32_e32 v20, 1.0, v20
	v_rcp_f32_e32 v20, v20
	v_mul_f32_e32 v19, v23, v21
	v_mul_f32_e32 v19, v22, v19
	v_mov_b32_e32 v21, v15
	v_mul_f32_e32 v17, v17, v20
	v_mul_f32_e32 v16, v16, v17
	v_cvt_pk_bf16_f32 v26, v16, v19
	v_fmamk_f32 v16, v150, 0x3a800000, v149
	v_mul_f32_e32 v17, 0x4b800000, v16
	v_cmp_gt_f32_e32 vcc, s48, v16
	v_cvt_pk_bf16_f32 v27, v18, v27
	v_mov_b32_e32 v20, v11
	s_nop 0
	v_cndmask_b32_e32 v16, v16, v17, vcc
	v_rsq_f32_e32 v18, v16
	v_add_co_u32_e64 v16, s[0:1], s49, v48
	v_mul_f32_e32 v19, 0x45800000, v18
	v_cndmask_b32_e32 v18, v18, v19, vcc
	v_pk_mul_f32 v[20:21], v[20:21], v[18:19] op_sel_hi:[1,0]
	v_addc_co_u32_e64 v17, s[0:1], 0, v49, s[0:1]
	v_mul_f32_e32 v11, 0xbfb8aa3b, v21
	v_exp_f32_e32 v15, v11
	v_mov_b32_e32 v11, v14
	v_pk_mul_f32 v[10:11], v[10:11], v[18:19] op_sel_hi:[1,0]
	global_store_dwordx4 v[16:17], v[24:27], off
	v_mul_f32_e32 v14, 0xbfb8aa3b, v11
	v_exp_f32_e32 v14, v14
	v_add_f32_e32 v15, 1.0, v15
	v_rcp_f32_e32 v19, v15
	v_mov_b32_e32 v15, v13
	v_add_f32_e32 v14, 1.0, v14
	v_rcp_f32_e32 v22, v14
	v_mov_b32_e32 v14, v9
	v_pk_mul_f32 v[14:15], v[14:15], v[18:19] op_sel_hi:[1,0]
	v_mul_f32_e32 v13, v21, v19
	v_mul_f32_e32 v9, 0xbfb8aa3b, v15
	v_exp_f32_e32 v9, v9
	v_mul_f32_e32 v11, v11, v22
	v_mul_f32_e32 v13, v20, v13
	v_mul_f32_e32 v20, v10, v11
	v_add_f32_e32 v9, 1.0, v9
	v_rcp_f32_e32 v19, v9
	v_mov_b32_e32 v9, v12
	v_mov_b32_e32 v11, v7
	s_andn2_b64 vcc, exec, s[6:7]
	v_pk_mul_f32 v[8:9], v[8:9], v[18:19] op_sel_hi:[1,0]
	v_mul_f32_e32 v10, v15, v19
	v_mul_f32_e32 v12, 0xbfb8aa3b, v9
	v_exp_f32_e32 v12, v12
	v_mul_f32_e32 v14, v14, v10
	s_mov_b64 s[0:1], -1
	v_add_f32_e32 v10, 1.0, v12
	v_rcp_f32_e32 v12, v10
	v_mov_b32_e32 v10, v3
	v_pk_mul_f32 v[10:11], v[10:11], v[18:19] op_sel_hi:[1,0]
	v_mul_f32_e32 v7, v9, v12
	v_mul_f32_e32 v3, 0xbfb8aa3b, v11
	v_exp_f32_e32 v3, v3
	v_mul_f32_e32 v7, v8, v7
	v_cvt_pk_bf16_f32 v8, v7, v14
	v_cvt_pk_bf16_f32 v9, v20, v13
	v_add_f32_e32 v3, 1.0, v3
	v_rcp_f32_e32 v7, v3
	v_mov_b32_e32 v3, v6
	v_pk_mul_f32 v[2:3], v[2:3], v[18:19] op_sel_hi:[1,0]
	v_mul_f32_e32 v7, v11, v7
	v_mul_f32_e32 v6, 0xbfb8aa3b, v3
	v_exp_f32_e32 v6, v6
	v_mul_f32_e32 v11, v10, v7
	v_mov_b32_e32 v7, v5
	v_add_f32_e32 v6, 1.0, v6
	v_rcp_f32_e32 v10, v6
	v_mov_b32_e32 v6, v1
	v_pk_mul_f32 v[6:7], v[6:7], v[18:19] op_sel_hi:[1,0]
	v_mul_f32_e32 v3, v3, v10
	v_mul_f32_e32 v1, 0xbfb8aa3b, v7
	v_exp_f32_e32 v5, v1
	v_mov_b32_e32 v1, v4
	v_pk_mul_f32 v[0:1], v[0:1], v[18:19] op_sel_hi:[1,0]
	v_mul_f32_e32 v2, v2, v3
	v_mul_f32_e32 v4, 0xbfb8aa3b, v1
	v_exp_f32_e32 v4, v4
	v_add_f32_e32 v5, 1.0, v5
	v_rcp_f32_e32 v5, v5
	v_add_f32_e32 v4, 1.0, v4
	v_rcp_f32_e32 v4, v4
	v_mul_f32_e32 v3, v7, v5
	v_mul_f32_e32 v3, v6, v3
	v_mul_f32_e32 v1, v1, v4
	v_mul_f32_e32 v0, v0, v1
	v_cvt_pk_bf16_f32 v10, v0, v3
	v_cvt_pk_bf16_f32 v11, v2, v11
	global_store_dwordx4 v[16:17], v[8:11], off offset:2048
	s_cbranch_vccnz .LBB0_1728
	s_andn2_b64 vcc, exec, s[8:9]
	s_cbranch_vccnz .LBB0_1727
	s_barrier
	s_branch .LBB0_1727
